# attnC: K tile global loads issued a full iteration before their LDS write (right after the previous tile's LDS write) instead of at the start of the S phase (on top of v49)
# baseline (speedup 1.0000x reference)
.LBB0_1086:
	s_lshl_b64 s[58:59], s[8:9], 10
	s_lshl_b64 s[64:65], s[8:9], 11
	v_mov_b32_e32 v245, v151
	s_lshl_b32 s8, s68, 7
	v_lshl_add_u64 v[0:1], s[62:63], 0, v[244:245]
	v_mov_b32_e32 v165, v151
	v_mov_b32_e32 v247, v151
	s_add_u32 s70, s62, s8
	v_lshl_add_u64 v[0:1], v[0:1], 0, v[164:165]
	v_lshl_add_u64 v[2:3], s[62:63], 0, v[246:247]
	s_addc_u32 s71, s63, 0
	v_lshl_add_u64 v[2:3], v[2:3], 0, v[164:165]
	global_load_dwordx4 v[32:35], v[0:1], off
	global_load_dwordx4 v[36:39], v[2:3], off
	v_lshl_add_u64 v[0:1], s[70:71], 0, v[244:245]
	v_lshl_add_u64 v[0:1], v[0:1], 0, v[164:165]
	v_lshl_add_u64 v[2:3], s[70:71], 0, v[246:247]
	v_lshl_add_u64 v[2:3], v[2:3], 0, v[164:165]
	global_load_dwordx4 v[40:43], v[0:1], off
	global_load_dwordx4 v[44:47], v[2:3], off
	v_accvgpr_read_b32 v0, a209
	v_mul_u32_u24_e32 v0, s68, v0
	v_lshlrev_b32_e32 v64, 1, v0
	v_mov_b32_e32 v65, v151
	v_mul_u32_u24_e32 v2, s68, v154
	v_lshl_add_u64 v[0:1], s[60:61], 0, v[64:65]
	v_lshlrev_b32_e32 v66, 1, v2
	v_mov_b32_e32 v67, v151
	v_lshl_add_u64 v[0:1], v[0:1], 0, v[164:165]
	v_lshl_add_u64 v[2:3], s[60:61], 0, v[66:67]
	v_lshl_add_u64 v[2:3], v[2:3], 0, v[164:165]
	global_load_dwordx4 v[48:51], v[0:1], off
	global_load_dwordx4 v[52:55], v[2:3], off
	v_mul_u32_u24_e32 v0, s68, v155
	v_lshlrev_b32_e32 v68, 1, v0
	v_mov_b32_e32 v69, v151
	v_mul_u32_u24_e32 v2, s68, v162
	v_lshl_add_u64 v[0:1], s[60:61], 0, v[68:69]
	v_lshlrev_b32_e32 v70, 1, v2
	v_mov_b32_e32 v71, v151
	v_lshl_add_u64 v[0:1], v[0:1], 0, v[164:165]
	v_lshl_add_u64 v[2:3], s[60:61], 0, v[70:71]
	v_lshl_add_u64 v[2:3], v[2:3], 0, v[164:165]
	global_load_dwordx4 v[56:59], v[0:1], off
	global_load_dwordx4 v[60:63], v[2:3], off
	v_mov_b32_e32 v251, v151
	v_lshl_add_u64 v[0:1], v[168:169], 0, s[64:65]
	v_lshl_add_u64 v[2:3], v[0:1], 0, v[150:151]
	v_lshl_add_u64 v[0:1], v[0:1], 0, v[250:251]
	global_load_dwordx4 v[28:31], v[2:3], off
	global_load_dwordx4 v[24:27], v[2:3], off offset:32
	global_load_dwordx4 v[20:23], v[2:3], off offset:64
	global_load_dwordx4 v[16:19], v[2:3], off offset:96
	global_load_dwordx4 v[12:15], v[0:1], off
	global_load_dwordx4 v[8:11], v[0:1], off offset:32
	global_load_dwordx4 v[4:7], v[0:1], off offset:64
	s_nop 0
	global_load_dwordx4 v[0:3], v[0:1], off offset:96
	v_lshl_add_u64 v[82:83], s[62:63], 0, v[170:171]
	v_lshl_add_u64 v[84:85], s[62:63], 0, v[242:243]
	v_lshl_add_u64 v[86:87], v[82:83], 0, s[8:9]
	v_lshl_add_u64 v[88:89], v[84:85], 0, s[8:9]
	s_add_i32 s8, s67, 1
	s_add_u32 s60, s60, 0x80
	v_mov_b32_e32 v80, 0
	s_addc_u32 s61, s61, 0
	v_accvgpr_write_b32 a31, 0
	v_accvgpr_write_b32 a30, 0
	v_accvgpr_write_b32 a29, 0
	v_accvgpr_write_b32 a28, 0
	v_accvgpr_write_b32 a27, 0
	v_accvgpr_write_b32 a26, 0
	v_accvgpr_write_b32 a25, 0
	v_accvgpr_write_b32 a24, 0
	v_accvgpr_write_b32 a23, 0
	v_accvgpr_write_b32 a22, 0
	v_lshl_add_u64 v[90:91], s[60:61], 0, v[64:65]
	v_lshl_add_u64 v[92:93], s[60:61], 0, v[66:67]
	v_lshl_add_u64 v[94:95], s[60:61], 0, v[68:69]
	v_lshl_add_u64 v[96:97], s[60:61], 0, v[70:71]
	v_accvgpr_write_b32 a21, 0
	v_accvgpr_write_b32 a20, 0
	v_accvgpr_write_b32 a19, 0
	v_accvgpr_write_b32 a18, 0
	v_accvgpr_write_b32 a17, 0
	v_accvgpr_write_b32 a16, 0
	v_accvgpr_write_b32 a111, 0
	v_accvgpr_write_b32 a110, 0
	v_accvgpr_write_b32 a109, 0
	v_accvgpr_write_b32 a108, 0
	v_accvgpr_write_b32 a107, 0
	v_accvgpr_write_b32 a106, 0
	v_accvgpr_write_b32 a105, 0
	v_accvgpr_write_b32 a104, 0
	v_accvgpr_write_b32 a103, 0
	v_accvgpr_write_b32 a102, 0
	v_accvgpr_write_b32 a101, 0
	v_accvgpr_write_b32 a100, 0
	v_accvgpr_write_b32 a99, 0
	v_accvgpr_write_b32 a98, 0
	v_accvgpr_write_b32 a97, 0
	v_accvgpr_write_b32 a96, 0
	v_accvgpr_write_b32 a143, 0
	v_accvgpr_write_b32 a142, 0
	v_accvgpr_write_b32 a141, 0
	v_accvgpr_write_b32 a140, 0
	v_accvgpr_write_b32 a139, 0
	v_accvgpr_write_b32 a138, 0
	v_accvgpr_write_b32 a137, 0
	v_accvgpr_write_b32 a136, 0
	v_accvgpr_write_b32 a135, 0
	v_accvgpr_write_b32 a134, 0
	v_accvgpr_write_b32 a133, 0
	v_accvgpr_write_b32 a132, 0
	v_accvgpr_write_b32 a131, 0
	v_accvgpr_write_b32 a130, 0
	v_accvgpr_write_b32 a129, 0
	v_accvgpr_write_b32 a128, 0
	v_accvgpr_write_b32 a63, 0
	v_accvgpr_write_b32 a62, 0
	v_accvgpr_write_b32 a61, 0
	v_accvgpr_write_b32 a60, 0
	v_accvgpr_write_b32 a59, 0
	v_accvgpr_write_b32 a58, 0
	v_accvgpr_write_b32 a57, 0
	v_accvgpr_write_b32 a56, 0
	v_accvgpr_write_b32 a55, 0
	v_accvgpr_write_b32 a54, 0
	v_accvgpr_write_b32 a53, 0
	v_accvgpr_write_b32 a52, 0
	v_accvgpr_write_b32 a51, 0
	v_accvgpr_write_b32 a50, 0
	v_accvgpr_write_b32 a49, 0
	v_accvgpr_write_b32 a48, 0
	v_accvgpr_write_b32 a95, 0
	v_accvgpr_write_b32 a94, 0
	v_accvgpr_write_b32 a93, 0
	v_accvgpr_write_b32 a92, 0
	v_accvgpr_write_b32 a91, 0
	v_accvgpr_write_b32 a90, 0
	v_accvgpr_write_b32 a89, 0
	v_accvgpr_write_b32 a88, 0
	v_accvgpr_write_b32 a87, 0
	v_accvgpr_write_b32 a86, 0
	v_accvgpr_write_b32 a85, 0
	v_accvgpr_write_b32 a84, 0
	v_accvgpr_write_b32 a83, 0
	v_accvgpr_write_b32 a82, 0
	v_accvgpr_write_b32 a81, 0
	v_accvgpr_write_b32 a80, 0
	v_accvgpr_write_b32 a47, 0
	v_accvgpr_write_b32 a46, 0
	v_accvgpr_write_b32 a45, 0
	v_accvgpr_write_b32 a44, 0
	v_accvgpr_write_b32 a43, 0
	v_accvgpr_write_b32 a42, 0
	v_accvgpr_write_b32 a41, 0
	v_accvgpr_write_b32 a40, 0
	v_accvgpr_write_b32 a39, 0
	v_accvgpr_write_b32 a38, 0
	v_accvgpr_write_b32 a37, 0
	v_accvgpr_write_b32 a36, 0
	v_accvgpr_write_b32 a35, 0
	v_accvgpr_write_b32 a34, 0
	v_accvgpr_write_b32 a33, 0
	v_accvgpr_write_b32 a32, 0
	v_accvgpr_write_b32 a127, 0
	v_accvgpr_write_b32 a126, 0
	v_accvgpr_write_b32 a125, 0
	v_accvgpr_write_b32 a124, 0
	v_accvgpr_write_b32 a123, 0
	v_accvgpr_write_b32 a122, 0
	v_accvgpr_write_b32 a121, 0
	v_accvgpr_write_b32 a120, 0
	v_accvgpr_write_b32 a119, 0
	v_accvgpr_write_b32 a118, 0
	v_accvgpr_write_b32 a117, 0
	v_accvgpr_write_b32 a116, 0
	v_accvgpr_write_b32 a115, 0
	v_accvgpr_write_b32 a114, 0
	v_accvgpr_write_b32 a113, 0
	v_accvgpr_write_b32 a112, 0
	v_accvgpr_write_b32 a79, 0
	v_accvgpr_write_b32 a78, 0
	v_accvgpr_write_b32 a77, 0
	v_accvgpr_write_b32 a76, 0
	v_accvgpr_write_b32 a75, 0
	v_accvgpr_write_b32 a74, 0
	v_accvgpr_write_b32 a73, 0
	v_accvgpr_write_b32 a72, 0
	v_accvgpr_write_b32 a71, 0
	v_accvgpr_write_b32 a70, 0
	v_accvgpr_write_b32 a69, 0
	v_accvgpr_write_b32 a68, 0
	v_accvgpr_write_b32 a67, 0
	v_accvgpr_write_b32 a66, 0
	v_accvgpr_write_b32 a65, 0
	v_accvgpr_write_b32 a64, 0
	s_mov_b32 s60, 0
	v_mov_b32_e32 v81, v80
	s_waitcnt vmcnt(15)
	ds_write_b128 v129, v[32:35]
	s_waitcnt vmcnt(14)
	ds_write_b128 v135, v[36:39]
	s_waitcnt vmcnt(13)
	ds_write_b128 v129, v[40:43] offset:9216
	s_waitcnt vmcnt(12)
	ds_write_b128 v135, v[44:47] offset:9216
	s_waitcnt vmcnt(11)
	ds_write_b128 v129, v[48:51] offset:36864
	s_waitcnt vmcnt(10)
	ds_write_b128 v135, v[52:55] offset:36864
	s_waitcnt vmcnt(9)
	ds_write_b128 v163, v[56:59] offset:36864
	s_waitcnt vmcnt(8)
	ds_write_b128 v166, v[60:63] offset:36864
	v_accvgpr_write_b32 a160, 0
	v_mov_b32_e32 v48, 0
	v_accvgpr_write_b32 a161, 0
	v_mov_b32_e32 v49, 0
	v_accvgpr_write_b32 a162, 0
	v_mov_b32_e32 v50, 0
	v_accvgpr_write_b32 a163, 0
	v_mov_b32_e32 v51, 0
	v_accvgpr_write_b32 a164, 0
	v_mov_b32_e32 v52, 0
	v_accvgpr_write_b32 a165, 0
	v_mov_b32_e32 v53, 0
	v_accvgpr_write_b32 a166, 0
	v_mov_b32_e32 v54, 0
	v_accvgpr_write_b32 a167, 0
	v_mov_b32_e32 v55, 0
	v_accvgpr_write_b32 a168, 0
	v_mov_b32_e32 v56, 0
	v_accvgpr_write_b32 a169, 0
	v_mov_b32_e32 v57, 0
	v_accvgpr_write_b32 a170, 0
	v_mov_b32_e32 v58, 0
	v_accvgpr_write_b32 a171, 0
	v_mov_b32_e32 v59, 0
	v_accvgpr_write_b32 a172, 0
	v_mov_b32_e32 v60, 0
	v_accvgpr_write_b32 a173, 0
	v_mov_b32_e32 v61, 0
	v_accvgpr_write_b32 a174, 0
	v_mov_b32_e32 v62, 0
	v_accvgpr_write_b32 a175, 0
	v_mov_b32_e32 v63, 0
	v_accvgpr_write_b32 a176, 0
	v_mov_b32_e32 v116, 0
	v_accvgpr_write_b32 a177, 0
	v_mov_b32_e32 v117, 0
	v_accvgpr_write_b32 a178, 0
	v_mov_b32_e32 v118, 0
	v_accvgpr_write_b32 a179, 0
	v_mov_b32_e32 v119, 0
	v_accvgpr_write_b32 a180, 0
	v_mov_b32_e32 v120, 0
	v_accvgpr_write_b32 a181, 0
	v_mov_b32_e32 v121, 0
	v_accvgpr_write_b32 a182, 0
	v_mov_b32_e32 v122, 0
	v_accvgpr_write_b32 a183, 0
	v_mov_b32_e32 v123, 0
	v_accvgpr_write_b32 a184, 0
	v_mov_b32_e32 v124, 0
	v_accvgpr_write_b32 a185, 0
	v_mov_b32_e32 v125, 0
	v_accvgpr_write_b32 a186, 0
	v_mov_b32_e32 v126, 0
	v_accvgpr_write_b32 a187, 0
	v_mov_b32_e32 v127, 0
	v_accvgpr_write_b32 a188, 0
	v_mov_b32_e32 v130, 0
	v_accvgpr_write_b32 a189, 0
	v_mov_b32_e32 v131, 0
	v_accvgpr_write_b32 a190, 0
	v_mov_b32_e32 v132, 0
	v_accvgpr_write_b32 a191, 0
	v_mov_b32_e32 v133, 0
	v_accvgpr_read_b32 v32, a0
	v_accvgpr_read_b32 v33, a0
	v_accvgpr_read_b32 v34, a0
	v_accvgpr_read_b32 v35, a0
	v_accvgpr_read_b32 v36, a0
	v_accvgpr_read_b32 v37, a0
	v_accvgpr_read_b32 v38, a0
	v_accvgpr_read_b32 v39, a0
	v_accvgpr_read_b32 v40, a0
	v_accvgpr_read_b32 v41, a0
	v_accvgpr_read_b32 v42, a0
	v_accvgpr_read_b32 v43, a0
	v_accvgpr_read_b32 v44, a0
	v_accvgpr_read_b32 v45, a0
	v_accvgpr_read_b32 v46, a0
	v_accvgpr_read_b32 v47, a0
	v_mbcnt_lo_u32_b32 v235, -1, 0
	v_mbcnt_hi_u32_b32 v235, -1, v235
	v_lshlrev_b32_e32 v235, 4, v235
	v_add_u32_e32 v235, 0xd800, v235
	s_waitcnt lgkmcnt(0)
	ds_write_b128 v235, a[160:163]
	ds_write_b128 v235, a[160:163] offset:1024
	ds_write_b128 v235, a[160:163] offset:2048
	ds_write_b128 v235, a[160:163] offset:3072
	ds_write_b128 v235, a[160:163] offset:4096
	ds_write_b128 v235, a[160:163] offset:5120
	ds_write_b128 v235, a[160:163] offset:6144
	ds_write_b128 v235, a[160:163] offset:7168
	ds_write_b128 v235, a[160:163] offset:8192
	s_waitcnt lgkmcnt(0)
	ds_write_b128 v235, a[160:163] offset:9216
	ds_write_b128 v235, a[160:163] offset:10240
	ds_write_b128 v235, a[160:163] offset:11264
	ds_write_b128 v235, a[160:163] offset:12288
	ds_write_b128 v235, a[160:163] offset:13312
	ds_write_b128 v235, a[160:163] offset:14336
	ds_write_b128 v235, a[160:163] offset:15360
	ds_write_b128 v235, a[160:163] offset:16384
	ds_write_b128 v235, a[160:163] offset:17408
	v_lshl_add_u64 v[98:99], v[82:83], 0, v[156:157]
	global_load_dwordx4 v[64:67], v[98:99], off
	v_lshl_add_u64 v[98:99], v[84:85], 0, v[156:157]
	global_load_dwordx4 v[68:71], v[98:99], off
	v_lshl_add_u64 v[98:99], v[86:87], 0, v[156:157]
	global_load_dwordx4 v[72:75], v[98:99], off
	v_lshl_add_u64 v[98:99], v[88:89], 0, v[156:157]
	global_load_dwordx4 v[76:79], v[98:99], off
	v_lshl_add_u64 v[82:83], v[82:83], 0, s[54:55]
	v_lshl_add_u64 v[84:85], v[84:85], 0, s[54:55]
	v_lshl_add_u64 v[86:87], v[86:87], 0, s[54:55]
	v_lshl_add_u64 v[88:89], v[88:89], 0, s[54:55]
.LBB0_1087:
	s_and_b32 s61, s60, 1
	s_xor_b32 s62, s61, 1
	s_mulk_i32 s61, 0x4800
	s_mulk_i32 s62, 0x4800
	v_add_u32_e32 v233, s61, v128
	v_add_u32_e32 v234, s62, v152
	s_waitcnt vmcnt(0) lgkmcnt(0)
	s_barrier
	ds_read_b128 a[144:147], v233
	ds_read_b128 a[148:151], v233 offset:32
	ds_read_b128 a[152:155], v233 offset:64
	ds_read_b128 a[156:159], v233 offset:96
	s_waitcnt lgkmcnt(3)
	v_mfma_f32_32x32x16_bf16 v[188:203], a[144:147], v[28:31], v[32:47]
	s_cmp_eq_u32 s60, 0
	s_cselect_b32 s32, 0x9000, s61
	v_add3_u32 v224, s32, v153, v134
	v_mfma_f32_32x32x16_bf16 v[172:187], a[144:147], v[12:15], v[32:47]
	v_add3_u32 v230, s32, v158, v134
	v_add3_u32 v231, s32, v159, v134
	v_add3_u32 v232, s32, v160, v134
	ds_read_b128 a[144:147], v233 offset:4608
	s_waitcnt lgkmcnt(3)
	v_mfma_f32_32x32x16_bf16 v[188:203], a[148:151], v[24:27], v[188:203]
	ds_write_b128 v224, v[140:143] offset:36864
	ds_write_b128 v230, v[144:147] offset:36864
	v_mfma_f32_32x32x16_bf16 v[172:187], a[148:151], v[8:11], v[172:187]
	ds_write_b128 v231, v[220:223] offset:36864
	ds_write_b128 v232, v[226:229] offset:36864
	v_accvgpr_write_b32 a160, v48
	ds_read_b128 a[148:151], v233 offset:4640
	s_waitcnt lgkmcnt(7)
	v_mfma_f32_32x32x16_bf16 v[188:203], a[152:155], v[20:23], v[188:203]
	v_accvgpr_write_b32 a161, v49
	v_accvgpr_write_b32 a162, v50
	v_accvgpr_write_b32 a163, v51
	v_mfma_f32_32x32x16_bf16 v[172:187], a[152:155], v[4:7], v[172:187]
	v_accvgpr_write_b32 a164, v52
	v_accvgpr_write_b32 a165, v53
	ds_read_b128 a[152:155], v233 offset:4672
	s_waitcnt lgkmcnt(7)
	v_mfma_f32_32x32x16_bf16 v[188:203], a[156:159], v[16:19], v[188:203]
	v_accvgpr_write_b32 a166, v54
	v_accvgpr_write_b32 a167, v55
	v_accvgpr_write_b32 a168, v56
	v_mfma_f32_32x32x16_bf16 v[172:187], a[156:159], v[0:3], v[172:187]
	v_accvgpr_write_b32 a169, v57
	v_accvgpr_write_b32 a170, v58
	ds_read_b128 a[156:159], v233 offset:4704
	s_waitcnt lgkmcnt(7)
	v_mfma_f32_32x32x16_bf16 v[204:219], a[144:147], v[28:31], v[32:47]
	v_accvgpr_write_b32 a171, v59
	v_accvgpr_write_b32 a172, v60
	v_accvgpr_write_b32 a173, v61
	v_mfma_f32_32x32x16_bf16 v[100:115], a[144:147], v[12:15], v[32:47]
	v_accvgpr_write_b32 a174, v62
	v_accvgpr_write_b32 a175, v63
	v_accvgpr_write_b32 a176, v116
	s_waitcnt lgkmcnt(2)
	v_mfma_f32_32x32x16_bf16 v[204:219], a[148:151], v[24:27], v[204:219]
	v_accvgpr_write_b32 a177, v117
	v_accvgpr_write_b32 a178, v118
	v_mfma_f32_32x32x16_bf16 v[100:115], a[148:151], v[8:11], v[100:115]
	v_accvgpr_write_b32 a179, v119
	v_accvgpr_write_b32 a180, v120
	v_accvgpr_write_b32 a181, v121
	s_waitcnt lgkmcnt(1)
	v_mfma_f32_32x32x16_bf16 v[204:219], a[152:155], v[20:23], v[204:219]
	v_accvgpr_write_b32 a182, v122
	v_accvgpr_write_b32 a183, v123
	v_accvgpr_write_b32 a184, v124
	v_mfma_f32_32x32x16_bf16 v[100:115], a[152:155], v[4:7], v[100:115]
	v_accvgpr_write_b32 a185, v125
	v_accvgpr_write_b32 a186, v126
	s_waitcnt lgkmcnt(0)
	v_mfma_f32_32x32x16_bf16 v[204:219], a[156:159], v[16:19], v[204:219]
	v_accvgpr_write_b32 a187, v127
	v_accvgpr_write_b32 a188, v130
	v_accvgpr_write_b32 a189, v131
	v_mfma_f32_32x32x16_bf16 v[100:115], a[156:159], v[0:3], v[100:115]
	v_accvgpr_write_b32 a190, v132
	v_accvgpr_write_b32 a191, v133
	ds_read_b128 a[144:147], v234 offset:36864
	ds_read_b128 a[148:151], v234 offset:36896
	ds_read_b128 a[152:155], v234 offset:36928
	ds_read_b128 a[156:159], v234 offset:36960
	s_waitcnt lgkmcnt(3)
	v_mfma_f32_32x32x16_bf16 a[128:143], a[144:147], a[160:163], a[128:143]
	v_exp_f32_e32 v188, v188
	v_exp_f32_e32 v189, v189
	v_exp_f32_e32 v190, v190
	v_exp_f32_e32 v191, v191
	v_mfma_f32_32x32x16_bf16 a[112:127], a[144:147], a[176:179], a[112:127]
	v_exp_f32_e32 v192, v192
	v_exp_f32_e32 v193, v193
	v_exp_f32_e32 v194, v194
	v_exp_f32_e32 v195, v195
	ds_read_b128 a[144:147], v234 offset:41472
	s_waitcnt lgkmcnt(3)
	v_mfma_f32_32x32x16_bf16 a[128:143], a[148:151], a[164:167], a[128:143]
	v_exp_f32_e32 v196, v196
	v_exp_f32_e32 v197, v197
	v_exp_f32_e32 v198, v198
	v_exp_f32_e32 v199, v199
	v_mfma_f32_32x32x16_bf16 a[112:127], a[148:151], a[180:183], a[112:127]
	v_exp_f32_e32 v200, v200
	v_exp_f32_e32 v201, v201
	v_exp_f32_e32 v202, v202
	v_exp_f32_e32 v203, v203
	ds_read_b128 a[148:151], v234 offset:41504
	s_waitcnt lgkmcnt(3)
	v_mfma_f32_32x32x16_bf16 a[128:143], a[152:155], a[168:171], a[128:143]
	v_pk_add_f32 v[136:137], v[188:189], v[190:191]
	v_pk_add_f32 v[136:137], v[136:137], v[192:193]
	v_pk_add_f32 v[136:137], v[136:137], v[194:195]
	v_pk_add_f32 v[136:137], v[136:137], v[196:197]
	v_mfma_f32_32x32x16_bf16 a[112:127], a[152:155], a[184:187], a[112:127]
	v_pk_add_f32 v[136:137], v[136:137], v[198:199]
	v_pk_add_f32 v[136:137], v[136:137], v[200:201]
	v_pk_add_f32 v[136:137], v[136:137], v[202:203]
	v_cvt_pk_bf16_f32 v48, v188, v189
	v_cvt_pk_bf16_f32 v49, v190, v191
	ds_read_b128 a[152:155], v234 offset:41536
	s_waitcnt lgkmcnt(3)
	v_mfma_f32_32x32x16_bf16 a[128:143], a[156:159], a[172:175], a[128:143]
	v_cvt_pk_bf16_f32 v50, v192, v193
	v_cvt_pk_bf16_f32 v51, v194, v195
	v_cvt_pk_bf16_f32 v52, v196, v197
	v_cvt_pk_bf16_f32 v53, v198, v199
	v_cvt_pk_bf16_f32 v54, v200, v201
	v_cvt_pk_bf16_f32 v55, v202, v203
	v_add3_u32 v224, s62, v153, v134
	v_add3_u32 v230, s62, v158, v134
	s_waitcnt vmcnt(3)
	v_mfma_f32_32x32x16_bf16 a[112:127], a[156:159], a[188:191], a[112:127]
	ds_write_b128 v224, v[64:67]
	s_waitcnt vmcnt(2)
	ds_write_b128 v230, v[68:71]
	s_waitcnt vmcnt(1)
	ds_write_b128 v224, v[72:75] offset:9216
	s_waitcnt vmcnt(0)
	ds_write_b128 v230, v[76:79] offset:9216
	ds_read_b128 a[156:159], v234 offset:41568
	s_waitcnt lgkmcnt(7)
	v_mfma_f32_32x32x16_bf16 a[48:63], a[144:147], a[160:163], a[48:63]
	v_lshl_add_u64 v[98:99], v[82:83], 0, v[156:157]
	global_load_dwordx4 v[64:67], v[98:99], off
	v_lshl_add_u64 v[98:99], v[84:85], 0, v[156:157]
	global_load_dwordx4 v[68:71], v[98:99], off
	v_lshl_add_u64 v[98:99], v[86:87], 0, v[156:157]
	global_load_dwordx4 v[72:75], v[98:99], off
	v_lshl_add_u64 v[98:99], v[88:89], 0, v[156:157]
	global_load_dwordx4 v[76:79], v[98:99], off
	v_mfma_f32_32x32x16_bf16 a[64:79], a[144:147], a[176:179], a[64:79]
	v_lshl_add_u64 v[82:83], v[82:83], 0, s[54:55]
	v_lshl_add_u64 v[84:85], v[84:85], 0, s[54:55]
	v_lshl_add_u64 v[86:87], v[86:87], 0, s[54:55]
	v_lshl_add_u64 v[88:89], v[88:89], 0, s[54:55]
	v_lshl_add_u64 v[98:99], v[90:91], 0, v[156:157]
	global_load_dwordx4 v[140:143], v[98:99], off
	v_lshl_add_u64 v[98:99], v[92:93], 0, v[156:157]
	global_load_dwordx4 v[144:147], v[98:99], off
	ds_read_b128 a[144:147], v234 offset:46080
	s_waitcnt lgkmcnt(7)
	v_mfma_f32_32x32x16_bf16 a[48:63], a[148:151], a[164:167], a[48:63]
	v_lshl_add_u64 v[98:99], v[94:95], 0, v[156:157]
	global_load_dwordx4 v[220:223], v[98:99], off
	v_lshl_add_u64 v[98:99], v[96:97], 0, v[156:157]
	global_load_dwordx4 v[226:229], v[98:99], off
	v_lshl_add_u64 v[90:91], v[90:91], 0, s[56:57]
	v_lshl_add_u64 v[92:93], v[92:93], 0, s[56:57]
	v_lshl_add_u64 v[94:95], v[94:95], 0, s[56:57]
	v_lshl_add_u64 v[96:97], v[96:97], 0, s[56:57]
	v_mfma_f32_32x32x16_bf16 a[64:79], a[148:151], a[180:183], a[64:79]
	v_exp_f32_e32 v172, v172
	v_exp_f32_e32 v173, v173
	v_exp_f32_e32 v174, v174
	v_exp_f32_e32 v175, v175
	ds_read_b128 a[148:151], v234 offset:46112
	s_waitcnt lgkmcnt(7)
	v_mfma_f32_32x32x16_bf16 a[48:63], a[152:155], a[168:171], a[48:63]
	v_exp_f32_e32 v176, v176
	v_exp_f32_e32 v177, v177
	v_exp_f32_e32 v178, v178
	v_exp_f32_e32 v179, v179
	v_mfma_f32_32x32x16_bf16 a[64:79], a[152:155], a[184:187], a[64:79]
	v_exp_f32_e32 v180, v180
	v_exp_f32_e32 v181, v181
	v_exp_f32_e32 v182, v182
	v_exp_f32_e32 v183, v183
	ds_read_b128 a[152:155], v234 offset:46144
	s_waitcnt lgkmcnt(3)
	v_mfma_f32_32x32x16_bf16 a[48:63], a[156:159], a[172:175], a[48:63]
	v_exp_f32_e32 v184, v184
	v_exp_f32_e32 v185, v185
	v_exp_f32_e32 v186, v186
	v_exp_f32_e32 v187, v187
	v_mfma_f32_32x32x16_bf16 a[64:79], a[156:159], a[188:191], a[64:79]
	v_pk_add_f32 v[148:149], v[172:173], v[174:175]
	v_pk_add_f32 v[148:149], v[148:149], v[176:177]
	v_pk_add_f32 v[148:149], v[148:149], v[178:179]
	v_pk_add_f32 v[148:149], v[148:149], v[180:181]
	ds_read_b128 a[156:159], v234 offset:46176
	s_waitcnt lgkmcnt(3)
	v_mfma_f32_32x32x16_bf16 a[80:95], a[144:147], a[160:163], a[80:95]
	v_pk_add_f32 v[148:149], v[148:149], v[182:183]
	v_pk_add_f32 v[148:149], v[148:149], v[184:185]
	v_pk_add_f32 v[148:149], v[148:149], v[186:187]
	v_cvt_pk_bf16_f32 v116, v172, v173
	v_cvt_pk_bf16_f32 v117, v174, v175
	v_cvt_pk_bf16_f32 v118, v176, v177
	v_mfma_f32_32x32x16_bf16 a[96:111], a[144:147], a[176:179], a[96:111]
	v_cvt_pk_bf16_f32 v119, v178, v179
	v_cvt_pk_bf16_f32 v120, v180, v181
	v_cvt_pk_bf16_f32 v121, v182, v183
	v_cvt_pk_bf16_f32 v122, v184, v185
	v_cvt_pk_bf16_f32 v123, v186, v187
	v_exp_f32_e32 v204, v204
	ds_read_b128 a[144:147], v234 offset:50688
	s_waitcnt lgkmcnt(3)
	v_mfma_f32_32x32x16_bf16 a[80:95], a[148:151], a[164:167], a[80:95]
	v_exp_f32_e32 v205, v205
	v_exp_f32_e32 v206, v206
	v_exp_f32_e32 v207, v207
	v_exp_f32_e32 v208, v208
	v_mfma_f32_32x32x16_bf16 a[96:111], a[148:151], a[180:183], a[96:111]
	v_exp_f32_e32 v209, v209
	v_exp_f32_e32 v210, v210
	v_exp_f32_e32 v211, v211
	v_exp_f32_e32 v212, v212
	ds_read_b128 a[148:151], v234 offset:50720
	s_waitcnt lgkmcnt(3)
	v_mfma_f32_32x32x16_bf16 a[80:95], a[152:155], a[168:171], a[80:95]
	v_exp_f32_e32 v213, v213
	v_exp_f32_e32 v214, v214
	v_exp_f32_e32 v215, v215
	v_exp_f32_e32 v216, v216
	v_mfma_f32_32x32x16_bf16 a[96:111], a[152:155], a[184:187], a[96:111]
	v_exp_f32_e32 v217, v217
	v_exp_f32_e32 v218, v218
	v_exp_f32_e32 v219, v219
	v_pk_add_f32 v[136:137], v[136:137], v[204:205]
	ds_read_b128 a[152:155], v234 offset:50752
	s_waitcnt lgkmcnt(3)
	v_mfma_f32_32x32x16_bf16 a[80:95], a[156:159], a[172:175], a[80:95]
	v_pk_add_f32 v[136:137], v[136:137], v[206:207]
	v_pk_add_f32 v[136:137], v[136:137], v[208:209]
	v_pk_add_f32 v[136:137], v[136:137], v[210:211]
	v_pk_add_f32 v[136:137], v[136:137], v[212:213]
	v_mfma_f32_32x32x16_bf16 a[96:111], a[156:159], a[188:191], a[96:111]
	v_pk_add_f32 v[136:137], v[136:137], v[214:215]
	v_pk_add_f32 v[136:137], v[136:137], v[216:217]
	v_pk_add_f32 v[136:137], v[136:137], v[218:219]
	v_cvt_pk_bf16_f32 v56, v204, v205
	v_cvt_pk_bf16_f32 v57, v206, v207
	v_cvt_pk_bf16_f32 v58, v208, v209
	ds_read_b128 a[156:159], v234 offset:50784
	s_waitcnt lgkmcnt(3)
	v_mfma_f32_32x32x16_bf16 a[32:47], a[144:147], a[160:163], a[32:47]
	v_cvt_pk_bf16_f32 v59, v210, v211
	v_cvt_pk_bf16_f32 v60, v212, v213
	v_cvt_pk_bf16_f32 v61, v214, v215
	v_cvt_pk_bf16_f32 v62, v216, v217
	v_cvt_pk_bf16_f32 v63, v218, v219
	v_add_f32_e32 v235, v136, v137
	v_add_f32_e32 v81, v81, v235
	v_mfma_f32_32x32x16_bf16 a[16:31], a[144:147], a[176:179], a[16:31]
	v_exp_f32_e32 v100, v100
	v_exp_f32_e32 v101, v101
	v_exp_f32_e32 v102, v102
	v_exp_f32_e32 v103, v103
	s_waitcnt lgkmcnt(2)
	v_mfma_f32_32x32x16_bf16 a[32:47], a[148:151], a[164:167], a[32:47]
	v_exp_f32_e32 v104, v104
	v_exp_f32_e32 v105, v105
	v_exp_f32_e32 v106, v106
	v_exp_f32_e32 v107, v107
	v_mfma_f32_32x32x16_bf16 a[16:31], a[148:151], a[180:183], a[16:31]
	v_exp_f32_e32 v108, v108
	v_exp_f32_e32 v109, v109
	v_exp_f32_e32 v110, v110
	v_exp_f32_e32 v111, v111
	s_waitcnt lgkmcnt(1)
	v_mfma_f32_32x32x16_bf16 a[32:47], a[152:155], a[168:171], a[32:47]
	v_exp_f32_e32 v112, v112
	v_exp_f32_e32 v113, v113
	v_exp_f32_e32 v114, v114
	v_exp_f32_e32 v115, v115
	v_mfma_f32_32x32x16_bf16 a[16:31], a[152:155], a[184:187], a[16:31]
	v_pk_add_f32 v[148:149], v[148:149], v[100:101]
	v_pk_add_f32 v[148:149], v[148:149], v[102:103]
	v_pk_add_f32 v[148:149], v[148:149], v[104:105]
	v_pk_add_f32 v[148:149], v[148:149], v[106:107]
	s_waitcnt lgkmcnt(0)
	v_mfma_f32_32x32x16_bf16 a[32:47], a[156:159], a[172:175], a[32:47]
	v_pk_add_f32 v[148:149], v[148:149], v[108:109]
	v_pk_add_f32 v[148:149], v[148:149], v[110:111]
	v_pk_add_f32 v[148:149], v[148:149], v[112:113]
	v_pk_add_f32 v[148:149], v[148:149], v[114:115]
	v_cvt_pk_bf16_f32 v124, v100, v101
	v_mfma_f32_32x32x16_bf16 a[16:31], a[156:159], a[188:191], a[16:31]
	v_cvt_pk_bf16_f32 v125, v102, v103
	v_cvt_pk_bf16_f32 v126, v104, v105
	v_cvt_pk_bf16_f32 v127, v106, v107
	v_cvt_pk_bf16_f32 v130, v108, v109
	v_cvt_pk_bf16_f32 v131, v110, v111
	v_cvt_pk_bf16_f32 v132, v112, v113
	v_cvt_pk_bf16_f32 v133, v114, v115
	v_add_f32_e32 v235, v148, v149
	v_add_f32_e32 v80, v80, v235
	s_add_i32 s60, s60, 1
	s_cmp_eq_u32 s8, s60
	s_cbranch_scc0 .LBB0_1087
	s_waitcnt vmcnt(0) lgkmcnt(0)
	s_barrier
	v_add3_u32 v224, s62, v153, v134
	v_add3_u32 v230, s62, v158, v134
	v_add3_u32 v231, s62, v159, v134
	v_add3_u32 v232, s62, v160, v134
	ds_write_b128 v224, v[140:143] offset:36864
	ds_write_b128 v230, v[144:147] offset:36864
	ds_write_b128 v231, v[220:223] offset:36864
	ds_write_b128 v232, v[226:229] offset:36864
	v_add_u32_e32 v234, s61, v152
	ds_read_b128 a[144:147], v234 offset:36864
	ds_read_b128 a[148:151], v234 offset:36896
	ds_read_b128 a[152:155], v234 offset:36928
	ds_read_b128 a[156:159], v234 offset:36960
	s_waitcnt lgkmcnt(3)
	v_mfma_f32_32x32x16_bf16 a[128:143], a[144:147], v[48:51], a[128:143]
	v_mfma_f32_32x32x16_bf16 a[112:127], a[144:147], v[116:119], a[112:127]
	ds_read_b128 a[144:147], v234 offset:41472
	s_waitcnt lgkmcnt(3)
	v_mfma_f32_32x32x16_bf16 a[128:143], a[148:151], v[52:55], a[128:143]
	v_mfma_f32_32x32x16_bf16 a[112:127], a[148:151], v[120:123], a[112:127]
	ds_read_b128 a[148:151], v234 offset:41504
	s_waitcnt lgkmcnt(3)
	v_mfma_f32_32x32x16_bf16 a[128:143], a[152:155], v[56:59], a[128:143]
	v_mfma_f32_32x32x16_bf16 a[112:127], a[152:155], v[124:127], a[112:127]
	ds_read_b128 a[152:155], v234 offset:41536
	s_waitcnt lgkmcnt(3)
	v_mfma_f32_32x32x16_bf16 a[128:143], a[156:159], v[60:63], a[128:143]
	v_mfma_f32_32x32x16_bf16 a[112:127], a[156:159], v[130:133], a[112:127]
	ds_read_b128 a[156:159], v234 offset:41568
	s_waitcnt lgkmcnt(3)
	v_mfma_f32_32x32x16_bf16 a[48:63], a[144:147], v[48:51], a[48:63]
	v_mfma_f32_32x32x16_bf16 a[64:79], a[144:147], v[116:119], a[64:79]
	ds_read_b128 a[144:147], v234 offset:46080
	s_waitcnt lgkmcnt(3)
	v_mfma_f32_32x32x16_bf16 a[48:63], a[148:151], v[52:55], a[48:63]
	v_mfma_f32_32x32x16_bf16 a[64:79], a[148:151], v[120:123], a[64:79]
	ds_read_b128 a[148:151], v234 offset:46112
	s_waitcnt lgkmcnt(3)
	v_mfma_f32_32x32x16_bf16 a[48:63], a[152:155], v[56:59], a[48:63]
	v_mfma_f32_32x32x16_bf16 a[64:79], a[152:155], v[124:127], a[64:79]
	ds_read_b128 a[152:155], v234 offset:46144
	s_waitcnt lgkmcnt(3)
	v_mfma_f32_32x32x16_bf16 a[48:63], a[156:159], v[60:63], a[48:63]
	v_mfma_f32_32x32x16_bf16 a[64:79], a[156:159], v[130:133], a[64:79]
	ds_read_b128 a[156:159], v234 offset:46176
	s_waitcnt lgkmcnt(3)
	v_mfma_f32_32x32x16_bf16 a[80:95], a[144:147], v[48:51], a[80:95]
	v_mfma_f32_32x32x16_bf16 a[96:111], a[144:147], v[116:119], a[96:111]
	ds_read_b128 a[144:147], v234 offset:50688
	s_waitcnt lgkmcnt(3)
	v_mfma_f32_32x32x16_bf16 a[80:95], a[148:151], v[52:55], a[80:95]
	v_mfma_f32_32x32x16_bf16 a[96:111], a[148:151], v[120:123], a[96:111]
	ds_read_b128 a[148:151], v234 offset:50720
	s_waitcnt lgkmcnt(3)
	v_mfma_f32_32x32x16_bf16 a[80:95], a[152:155], v[56:59], a[80:95]
	v_mfma_f32_32x32x16_bf16 a[96:111], a[152:155], v[124:127], a[96:111]
	ds_read_b128 a[152:155], v234 offset:50752
	s_waitcnt lgkmcnt(3)
	v_mfma_f32_32x32x16_bf16 a[80:95], a[156:159], v[60:63], a[80:95]
	v_mfma_f32_32x32x16_bf16 a[96:111], a[156:159], v[130:133], a[96:111]
	ds_read_b128 a[156:159], v234 offset:50784
	s_waitcnt lgkmcnt(3)
	v_mfma_f32_32x32x16_bf16 a[32:47], a[144:147], v[48:51], a[32:47]
	v_mfma_f32_32x32x16_bf16 a[16:31], a[144:147], v[116:119], a[16:31]
	s_waitcnt lgkmcnt(2)
	v_mfma_f32_32x32x16_bf16 a[32:47], a[148:151], v[52:55], a[32:47]
	v_mfma_f32_32x32x16_bf16 a[16:31], a[148:151], v[120:123], a[16:31]
	s_waitcnt lgkmcnt(1)
	v_mfma_f32_32x32x16_bf16 a[32:47], a[152:155], v[56:59], a[32:47]
	v_mfma_f32_32x32x16_bf16 a[16:31], a[152:155], v[124:127], a[16:31]
	s_waitcnt lgkmcnt(0)
	v_mfma_f32_32x32x16_bf16 a[32:47], a[156:159], v[60:63], a[32:47]
	v_mfma_f32_32x32x16_bf16 a[16:31], a[156:159], v[130:133], a[16:31]
	s_bitcmp1_b32 s8, 0
	s_cselect_b32 s8, 0x4800, 0
	v_add_u32_e32 v48, s8, v128
	s_waitcnt lgkmcnt(0)
	s_barrier
	ds_read_b128 v[32:35], v48
	ds_read_b128 v[36:39], v48 offset:32
	s_waitcnt lgkmcnt(1)
	v_mfma_f32_32x32x16_bf16 a[186:201], v[32:35], v[28:31], a[0:15]
	v_add_u32_e32 v83, s8, v152
	v_mfma_f32_32x32x16_bf16 a[144:159], v[32:35], v[12:15], a[0:15]
	s_waitcnt lgkmcnt(0)
	v_mfma_f32_32x32x16_bf16 a[186:201], v[36:39], v[24:27], a[186:201]
	v_mfma_f32_32x32x16_bf16 a[144:159], v[36:39], v[8:11], a[144:159]
	ds_read_b128 v[32:35], v48 offset:64
	ds_read_b128 v[36:39], v48 offset:96
	s_waitcnt lgkmcnt(1)
	v_mfma_f32_32x32x16_bf16 a[186:201], v[32:35], v[20:23], a[186:201]
	s_waitcnt lgkmcnt(0)
	v_mfma_f32_32x32x16_bf16 a[186:201], v[36:39], v[16:19], a[186:201]
	v_mfma_f32_32x32x16_bf16 a[144:159], v[32:35], v[4:7], a[144:159]
	ds_read_b128 v[32:35], v48 offset:4608
	ds_read_b128 v[40:43], v48 offset:4640
	ds_read_b128 v[44:47], v48 offset:4672
	ds_read_b128 v[48:51], v48 offset:4704
	s_nop 6
	v_accvgpr_read_b32 v52, a186
	v_accvgpr_read_b32 v53, a187
	v_accvgpr_read_b32 v54, a188
	v_exp_f32_e32 v52, v52
	v_exp_f32_e32 v53, v53
	s_waitcnt lgkmcnt(3)
	v_mfma_f32_32x32x16_bf16 a[172:187], v[32:35], v[28:31], a[0:15]
	v_accvgpr_read_b32 v28, a189
	v_exp_f32_e32 v55, v28
	v_accvgpr_read_b32 v28, a190
	v_exp_f32_e32 v56, v28
	v_accvgpr_read_b32 v28, a191
	v_exp_f32_e32 v54, v54
	v_exp_f32_e32 v57, v28
	s_waitcnt lgkmcnt(2)
	v_mfma_f32_32x32x16_bf16 a[172:187], v[40:43], v[24:27], a[172:187]
	v_accvgpr_read_b32 v24, a192
	v_exp_f32_e32 v58, v24
	v_accvgpr_read_b32 v24, a193
	v_exp_f32_e32 v59, v24
	v_accvgpr_read_b32 v24, a194
	v_exp_f32_e32 v60, v24
	v_accvgpr_read_b32 v24, a195
	s_waitcnt lgkmcnt(1)
	v_mfma_f32_32x32x16_bf16 a[172:187], v[44:47], v[20:23], a[172:187]
	v_accvgpr_read_b32 v20, a196
	v_exp_f32_e32 v62, v20
	v_accvgpr_read_b32 v20, a197
	v_exp_f32_e32 v63, v20
	v_accvgpr_read_b32 v20, a198
	v_exp_f32_e32 v64, v20
	v_exp_f32_e32 v61, v24
	s_waitcnt lgkmcnt(0)
	v_mfma_f32_32x32x16_bf16 a[172:187], v[48:51], v[16:19], a[172:187]
	v_accvgpr_read_b32 v16, a199
	v_exp_f32_e32 v65, v16
	v_accvgpr_read_b32 v16, a200
	v_exp_f32_e32 v66, v16
	v_accvgpr_read_b32 v16, a201
	v_exp_f32_e32 v67, v16
	ds_read_b128 v[28:31], v83 offset:36928
	v_mfma_f32_32x32x16_bf16 a[144:159], v[36:39], v[0:3], a[144:159]
	s_nop 3
	v_accvgpr_read_b32 v16, a172
	v_exp_f32_e32 v36, v16
	v_accvgpr_read_b32 v16, a173
	v_exp_f32_e32 v37, v16
	v_accvgpr_read_b32 v16, a174
	v_exp_f32_e32 v38, v16
	v_accvgpr_read_b32 v16, a175
	v_mfma_f32_32x32x16_bf16 a[160:175], v[32:35], v[12:15], a[0:15]
	v_exp_f32_e32 v39, v16
	v_accvgpr_read_b32 v16, a144
	v_accvgpr_read_b32 v12, a176
	v_exp_f32_e32 v68, v12
	v_accvgpr_read_b32 v12, a177
	v_accvgpr_read_b32 v20, a157
	v_exp_f32_e32 v69, v12
	v_mfma_f32_32x32x16_bf16 a[160:175], v[40:43], v[8:11], a[160:175]
	v_accvgpr_read_b32 v12, a178
	v_exp_f32_e32 v84, v20
	v_accvgpr_read_b32 v20, a158
	v_exp_f32_e32 v70, v12
	v_accvgpr_read_b32 v12, a179
	v_exp_f32_e32 v85, v20
	v_accvgpr_read_b32 v20, a159
	v_mfma_f32_32x32x16_bf16 a[160:175], v[44:47], v[4:7], a[160:175]
	v_exp_f32_e32 v40, v12
	v_cvt_pk_bf16_f32 v12, v52, v53
	v_cvt_pk_bf16_f32 v13, v54, v55
	v_cvt_pk_bf16_f32 v14, v56, v57
	v_cvt_pk_bf16_f32 v15, v58, v59
	v_exp_f32_e32 v86, v20
	ds_read_b128 v[20:23], v83 offset:36896
	v_mfma_f32_32x32x16_bf16 a[160:175], v[48:51], v[0:3], a[160:175]
	v_exp_f32_e32 v49, v16
	v_accvgpr_read_b32 v16, a145
	v_exp_f32_e32 v50, v16
	v_accvgpr_read_b32 v16, a146
	v_exp_f32_e32 v51, v16
	v_accvgpr_read_b32 v16, a147
	v_exp_f32_e32 v71, v16
	v_accvgpr_read_b32 v16, a148
	v_exp_f32_e32 v72, v16
	v_accvgpr_read_b32 v16, a149
	v_exp_f32_e32 v73, v16
	v_accvgpr_read_b32 v16, a150
	v_exp_f32_e32 v74, v16
	v_accvgpr_read_b32 v16, a151
	v_exp_f32_e32 v75, v16
	v_accvgpr_read_b32 v16, a152
	v_exp_f32_e32 v76, v16
	v_accvgpr_read_b32 v16, a153
	v_exp_f32_e32 v77, v16
	v_accvgpr_read_b32 v16, a154
	v_exp_f32_e32 v78, v16
	v_accvgpr_read_b32 v16, a155
	v_exp_f32_e32 v79, v16
	v_accvgpr_read_b32 v16, a156
	v_exp_f32_e32 v82, v16
	ds_read_b128 v[16:19], v83 offset:36864
	v_accvgpr_read_b32 v24, a160
	v_exp_f32_e32 v87, v24
	v_accvgpr_read_b32 v24, a161
	v_exp_f32_e32 v88, v24
	v_cvt_pk_bf16_f32 v24, v49, v50
	v_cvt_pk_bf16_f32 v25, v51, v71
	v_cvt_pk_bf16_f32 v26, v72, v73
	v_cvt_pk_bf16_f32 v27, v74, v75
	s_waitcnt lgkmcnt(0)
	v_mfma_f32_32x32x16_bf16 a[144:159], v[16:19], v[12:15], a[128:143]
	v_accvgpr_read_b32 v8, a180
	v_exp_f32_e32 v41, v8
	v_accvgpr_read_b32 v8, a181
	v_exp_f32_e32 v42, v8
	v_accvgpr_read_b32 v8, a182
	v_exp_f32_e32 v43, v8
	v_cvt_pk_bf16_f32 v8, v60, v61
	v_mfma_f32_32x32x16_bf16 a[128:143], v[16:19], v[24:27], a[112:127]
	v_accvgpr_read_b32 v16, a162
	v_exp_f32_e32 v89, v16
	v_accvgpr_read_b32 v16, a163
	v_exp_f32_e32 v90, v16
	v_accvgpr_read_b32 v16, a164
	v_exp_f32_e32 v91, v16
	v_accvgpr_read_b32 v16, a165
	v_cvt_pk_bf16_f32 v9, v62, v63
	v_cvt_pk_bf16_f32 v10, v64, v65
	v_cvt_pk_bf16_f32 v11, v66, v67
	v_exp_f32_e32 v92, v16
	v_cvt_pk_bf16_f32 v16, v76, v77
	v_cvt_pk_bf16_f32 v17, v78, v79
	v_cvt_pk_bf16_f32 v18, v82, v84
	v_cvt_pk_bf16_f32 v19, v85, v86
	v_mfma_f32_32x32x16_bf16 a[144:159], v[20:23], v[8:11], a[144:159]
	v_accvgpr_read_b32 v32, a166
	v_accvgpr_read_b32 v4, a183
	v_exp_f32_e32 v93, v32
	v_exp_f32_e32 v44, v4
	v_accvgpr_read_b32 v4, a184
	v_exp_f32_e32 v45, v4
	v_accvgpr_read_b32 v4, a185
	v_mfma_f32_32x32x16_bf16 a[128:143], v[20:23], v[16:19], a[128:143]
	v_accvgpr_read_b32 v20, a167
	v_exp_f32_e32 v94, v20
	v_accvgpr_read_b32 v32, a169
	v_exp_f32_e32 v46, v4
	v_accvgpr_read_b32 v4, a186
	v_exp_f32_e32 v96, v32
	v_accvgpr_read_b32 v32, a170
	v_exp_f32_e32 v47, v4
	v_cvt_pk_bf16_f32 v4, v36, v37
	v_cvt_pk_bf16_f32 v5, v38, v39
	v_cvt_pk_bf16_f32 v6, v68, v69
	v_cvt_pk_bf16_f32 v7, v70, v40
	v_accvgpr_read_b32 v20, a168
	v_exp_f32_e32 v97, v32
	v_cvt_pk_bf16_f32 v32, v87, v88
	v_cvt_pk_bf16_f32 v33, v89, v90
	v_cvt_pk_bf16_f32 v34, v91, v92
	v_cvt_pk_bf16_f32 v35, v93, v94
	v_exp_f32_e32 v95, v20
	ds_read_b128 v[20:23], v83 offset:36960
	v_mfma_f32_32x32x16_bf16 a[144:159], v[28:31], v[4:7], a[144:159]
	v_accvgpr_read_b32 v0, a187
	v_exp_f32_e32 v48, v0
	v_cvt_pk_bf16_f32 v0, v41, v42
	v_cvt_pk_bf16_f32 v1, v43, v44
	v_cvt_pk_bf16_f32 v2, v45, v46
	v_cvt_pk_bf16_f32 v3, v47, v48
	v_cvt_pk_bf16_f32 v130, v95, v96
	v_mfma_f32_32x32x16_bf16 a[128:143], v[28:31], v[32:35], a[128:143]
	v_accvgpr_read_b32 v28, a171
	v_exp_f32_e32 v98, v28
	v_accvgpr_read_b32 v28, a172
	v_exp_f32_e32 v99, v28
	v_accvgpr_read_b32 v28, a173
	v_exp_f32_e32 v100, v28
	v_accvgpr_read_b32 v28, a174
	v_exp_f32_e32 v101, v28
	v_accvgpr_read_b32 v28, a175
	v_exp_f32_e32 v102, v28
	v_cvt_pk_bf16_f32 v131, v97, v98
	v_cvt_pk_bf16_f32 v132, v99, v100
	s_waitcnt lgkmcnt(0)
	v_mfma_f32_32x32x16_bf16 a[144:159], v[20:23], v[0:3], a[144:159]
	v_cvt_pk_bf16_f32 v133, v101, v102
	s_nop 1
	v_mfma_f32_32x32x16_bf16 a[128:143], v[20:23], v[130:133], a[128:143]
	ds_read_b128 v[20:23], v83 offset:41472
	ds_read_b128 v[28:31], v83 offset:41504
	s_nop 5
	v_accvgpr_read_b32 v112, a144
	v_accvgpr_read_b32 v113, a145
	v_accvgpr_read_b32 v114, a146
	v_accvgpr_read_b32 v115, a147
	s_waitcnt lgkmcnt(1)
	v_mfma_f32_32x32x16_bf16 a[112:127], v[20:23], v[12:15], a[48:63]
	v_accvgpr_read_b32 v116, a148
	v_accvgpr_read_b32 v117, a149
	v_accvgpr_read_b32 v118, a150
	v_accvgpr_read_b32 v119, a151
	v_accvgpr_read_b32 v120, a152
	v_accvgpr_read_b32 v121, a153
	v_accvgpr_read_b32 v122, a154
	v_mfma_f32_32x32x16_bf16 a[48:63], v[20:23], v[24:27], a[64:79]
	v_accvgpr_read_b32 v123, a155
	v_accvgpr_read_b32 v124, a156
	v_accvgpr_read_b32 v125, a157
	v_accvgpr_read_b32 v126, a158
	v_accvgpr_read_b32 v127, a159
	s_waitcnt lgkmcnt(0)
	v_mfma_f32_32x32x16_bf16 a[112:127], v[28:31], v[8:11], a[112:127]
	v_mfma_f32_32x32x16_bf16 a[48:63], v[28:31], v[16:19], a[48:63]
	ds_read_b128 v[20:23], v83 offset:41536
	ds_read_b128 v[28:31], v83 offset:41568
	s_waitcnt lgkmcnt(1)
	v_mfma_f32_32x32x16_bf16 a[112:127], v[20:23], v[4:7], a[112:127]
	v_mfma_f32_32x32x16_bf16 a[48:63], v[20:23], v[32:35], a[48:63]
	s_waitcnt lgkmcnt(0)
	v_mfma_f32_32x32x16_bf16 a[112:127], v[28:31], v[0:3], a[112:127]
	v_mfma_f32_32x32x16_bf16 a[48:63], v[28:31], v[130:133], a[48:63]
	ds_read_b128 v[20:23], v83 offset:46080
	ds_read_b128 v[28:31], v83 offset:46112
	s_waitcnt lgkmcnt(1)
	v_mfma_f32_32x32x16_bf16 a[64:79], v[20:23], v[12:15], a[80:95]
	v_mfma_f32_32x32x16_bf16 a[80:95], v[20:23], v[24:27], a[96:111]
	ds_read_b128 v[20:23], v83 offset:46144
	s_waitcnt lgkmcnt(1)
	v_mfma_f32_32x32x16_bf16 a[64:79], v[28:31], v[8:11], a[64:79]
	v_mfma_f32_32x32x16_bf16 a[80:95], v[28:31], v[16:19], a[80:95]
	v_add_f32_e32 v28, 0, v52
	v_add_f32_e32 v28, v53, v28
	v_add_f32_e32 v28, v54, v28
	v_add_f32_e32 v28, v55, v28
	v_add_f32_e32 v52, v56, v28
	v_add_f32_e32 v52, v57, v52
	v_add_f32_e32 v52, v58, v52
	v_add_f32_e32 v52, v59, v52
	v_add_f32_e32 v52, v60, v52
	v_add_f32_e32 v52, v61, v52
	v_add_f32_e32 v52, v62, v52
	v_add_f32_e32 v52, v63, v52
	ds_read_b128 v[28:31], v83 offset:46176
	s_waitcnt lgkmcnt(1)
	v_mfma_f32_32x32x16_bf16 a[64:79], v[20:23], v[4:7], a[64:79]
	v_mfma_f32_32x32x16_bf16 a[80:95], v[20:23], v[32:35], a[80:95]
	v_add_f32_e32 v20, v64, v52
	v_add_f32_e32 v20, v65, v20
	v_add_f32_e32 v20, v66, v20
	v_add_f32_e32 v20, v67, v20
	v_add_f32_e32 v20, v36, v20
	v_add_f32_e32 v20, v37, v20
	v_add_f32_e32 v20, v38, v20
	v_add_f32_e32 v20, v39, v20
	v_add_f32_e32 v20, v68, v20
	v_add_f32_e32 v20, v69, v20
	v_add_f32_e32 v20, v70, v20
	v_add_f32_e32 v20, v40, v20
	v_add_f32_e32 v36, v41, v20
	ds_read_b128 v[20:23], v83 offset:50688
	s_waitcnt lgkmcnt(1)
	v_mfma_f32_32x32x16_bf16 a[64:79], v[28:31], v[0:3], a[64:79]
	v_mfma_f32_32x32x16_bf16 a[80:95], v[28:31], v[130:133], a[80:95]
	v_add_f32_e32 v28, v42, v36
	v_add_f32_e32 v28, v43, v28
	v_add_f32_e32 v28, v44, v28
	v_add_f32_e32 v28, v45, v28
	v_add_f32_e32 v28, v46, v28
	v_add_f32_e32 v36, v47, v28
	ds_read_b128 v[28:31], v83 offset:50720
	s_waitcnt lgkmcnt(1)
	v_mfma_f32_32x32x16_bf16 a[96:111], v[20:23], v[12:15], a[32:47]
	v_add_f32_e32 v12, v48, v36
	v_add_f32_e32 v136, v81, v12
	v_add_f32_e32 v12, 0, v49
	v_add_f32_e32 v12, v50, v12
	v_add_f32_e32 v12, v51, v12
	v_add_f32_e32 v12, v71, v12
	v_add_f32_e32 v12, v72, v12
	v_add_f32_e32 v12, v73, v12
	v_add_f32_e32 v12, v74, v12
	v_add_f32_e32 v12, v75, v12
	v_add_f32_e32 v12, v76, v12
	v_add_f32_e32 v12, v77, v12
	v_add_f32_e32 v12, v78, v12
	v_add_f32_e32 v12, v79, v12
	s_waitcnt lgkmcnt(0)
	v_mfma_f32_32x32x16_bf16 a[96:111], v[28:31], v[8:11], a[96:111]
	v_add_f32_e32 v8, v82, v12
	v_add_f32_e32 v8, v84, v8
	v_add_f32_e32 v8, v85, v8
	v_add_f32_e32 v8, v86, v8
	v_add_f32_e32 v8, v87, v8
	v_add_f32_e32 v12, v88, v8
	ds_read_b128 v[8:11], v83 offset:50752
	v_mfma_f32_32x32x16_bf16 a[32:47], v[20:23], v[24:27], a[16:31]
	v_add_f32_e32 v12, v89, v12
	v_add_f32_e32 v12, v90, v12
	v_add_f32_e32 v12, v91, v12
	v_add_f32_e32 v12, v92, v12
	v_add_f32_e32 v12, v93, v12
	v_accvgpr_read_b32 v48, a128
	v_accvgpr_read_b32 v49, a129
	v_mfma_f32_32x32x16_bf16 a[32:47], v[28:31], v[16:19], a[32:47]
	v_add_f32_e32 v16, v94, v12
	ds_read_b128 v[12:15], v83 offset:50784
	v_accvgpr_read_b32 v50, a130
	v_accvgpr_read_b32 v51, a131
	v_accvgpr_read_b32 v52, a132
	v_accvgpr_read_b32 v53, a133
	v_accvgpr_read_b32 v54, a134
	s_waitcnt lgkmcnt(1)
	v_mfma_f32_32x32x16_bf16 a[96:111], v[8:11], v[4:7], a[96:111]
	v_add_f32_e32 v4, v95, v16
	v_add_f32_e32 v4, v96, v4
	v_add_f32_e32 v4, v97, v4
	v_add_f32_e32 v4, v98, v4
	v_add_f32_e32 v4, v99, v4
	v_add_f32_e32 v4, v100, v4
	v_add_f32_e32 v4, v101, v4
	v_add_f32_e32 v4, v102, v4
	v_add_f32_e32 v137, v80, v4
	ds_bpermute_b32 v4, v161, v136
	v_mfma_f32_32x32x16_bf16 a[32:47], v[8:11], v[32:35], a[32:47]
	v_accvgpr_read_b32 v96, a112
	v_accvgpr_read_b32 v32, a48
	v_accvgpr_read_b32 v95, a79
	s_waitcnt lgkmcnt(0)
	v_add_f32_e32 v136, v136, v4
	v_div_scale_f32 v140, s[60:61], v136, v136, 1.0
	v_rcp_f32_e32 v141, v140
	v_mfma_f32_32x32x16_bf16 a[32:47], v[12:15], v[130:133], a[32:47]
	ds_bpermute_b32 v131, v161, v137
	v_accvgpr_read_b32 v16, a80
	v_fma_f32 v130, -v140, v141, 1.0
	v_fmac_f32_e32 v141, v130, v141
	v_div_scale_f32 v130, vcc, 1.0, v136, 1.0
	v_mul_f32_e32 v132, v130, v141
	v_fma_f32 v133, -v140, v132, v130
	s_waitcnt lgkmcnt(0)
	v_add_f32_e32 v131, v137, v131
	v_fmac_f32_e32 v132, v133, v141
	v_div_scale_f32 v133, s[60:61], v131, v131, 1.0
	v_rcp_f32_e32 v137, v133
	v_mfma_f32_32x32x16_bf16 a[96:111], v[12:15], v[0:3], a[96:111]
	v_fma_f32 v130, -v140, v132, v130
	v_div_fmas_f32 v130, v130, v141, v132
	v_div_fixup_f32 v224, v130, v136, 1.0
	v_fma_f32 v130, -v133, v137, 1.0
	v_fmac_f32_e32 v137, v130, v137
	v_div_scale_f32 v130, vcc, 1.0, v131, 1.0
	v_mul_f32_e32 v132, v130, v137
	v_fma_f32 v136, -v133, v132, v130
	v_fmac_f32_e32 v132, v136, v137
	v_fma_f32 v130, -v133, v132, v130
	v_accvgpr_read_b32 v0, a32
	s_nop 0
	v_accvgpr_read_b32 v64, a96
	v_div_fmas_f32 v130, v130, v137, v132
	v_accvgpr_read_b32 v55, a135
	v_accvgpr_read_b32 v56, a136
	v_accvgpr_read_b32 v57, a137
	v_accvgpr_read_b32 v58, a138
	v_accvgpr_read_b32 v59, a139
	v_accvgpr_read_b32 v60, a140
	v_accvgpr_read_b32 v61, a141
	v_accvgpr_read_b32 v62, a142
	v_accvgpr_read_b32 v63, a143
	v_accvgpr_read_b32 v97, a113
	v_accvgpr_read_b32 v98, a114
	v_accvgpr_read_b32 v99, a115
	v_accvgpr_read_b32 v100, a116
	v_accvgpr_read_b32 v101, a117
	v_accvgpr_read_b32 v102, a118
	v_accvgpr_read_b32 v103, a119
	v_accvgpr_read_b32 v104, a120
	v_accvgpr_read_b32 v105, a121
	v_accvgpr_read_b32 v106, a122
	v_accvgpr_read_b32 v107, a123
	v_accvgpr_read_b32 v108, a124
	v_accvgpr_read_b32 v109, a125
	v_accvgpr_read_b32 v110, a126
	v_accvgpr_read_b32 v111, a127
	v_accvgpr_read_b32 v33, a49
	v_accvgpr_read_b32 v34, a50
	v_accvgpr_read_b32 v35, a51
	v_accvgpr_read_b32 v36, a52
	v_accvgpr_read_b32 v37, a53
	v_accvgpr_read_b32 v38, a54
	v_accvgpr_read_b32 v39, a55
	v_accvgpr_read_b32 v40, a56
	v_accvgpr_read_b32 v41, a57
	v_accvgpr_read_b32 v42, a58
	v_accvgpr_read_b32 v43, a59
	v_accvgpr_read_b32 v44, a60
	v_accvgpr_read_b32 v45, a61
	v_accvgpr_read_b32 v46, a62
	v_accvgpr_read_b32 v47, a63
	v_accvgpr_read_b32 v94, a78
	v_accvgpr_read_b32 v93, a77
	v_accvgpr_read_b32 v92, a76
	v_accvgpr_read_b32 v91, a75
	v_accvgpr_read_b32 v90, a74
	v_accvgpr_read_b32 v89, a73
	v_accvgpr_read_b32 v88, a72
	v_accvgpr_read_b32 v87, a71
	v_accvgpr_read_b32 v86, a70
	v_accvgpr_read_b32 v85, a69
	v_accvgpr_read_b32 v84, a68
	v_accvgpr_read_b32 v83, a67
	v_accvgpr_read_b32 v82, a66
	v_accvgpr_read_b32 v81, a65
	v_accvgpr_read_b32 v80, a64
	v_accvgpr_read_b32 v17, a81
	v_accvgpr_read_b32 v18, a82
	v_accvgpr_read_b32 v19, a83
	v_accvgpr_read_b32 v20, a84
	v_accvgpr_read_b32 v21, a85
	v_accvgpr_read_b32 v22, a86
	v_accvgpr_read_b32 v23, a87
	v_accvgpr_read_b32 v24, a88
	v_accvgpr_read_b32 v25, a89
	v_accvgpr_read_b32 v26, a90
	v_accvgpr_read_b32 v27, a91
	v_accvgpr_read_b32 v28, a92
	v_accvgpr_read_b32 v29, a93
	v_accvgpr_read_b32 v30, a94
	v_accvgpr_read_b32 v31, a95
	v_accvgpr_read_b32 v65, a97
	v_accvgpr_read_b32 v66, a98
	v_accvgpr_read_b32 v67, a99
	v_accvgpr_read_b32 v68, a100
	v_accvgpr_read_b32 v69, a101
	v_accvgpr_read_b32 v70, a102
	v_accvgpr_read_b32 v71, a103
	v_accvgpr_read_b32 v72, a104
	v_accvgpr_read_b32 v73, a105
	v_accvgpr_read_b32 v74, a106
	v_accvgpr_read_b32 v75, a107
	v_accvgpr_read_b32 v76, a108
	v_accvgpr_read_b32 v77, a109
	v_accvgpr_read_b32 v78, a110
	v_accvgpr_read_b32 v79, a111
	v_accvgpr_read_b32 v1, a33
	v_accvgpr_read_b32 v2, a34
	v_accvgpr_read_b32 v3, a35
	v_accvgpr_read_b32 v4, a36
	v_accvgpr_read_b32 v5, a37
	v_accvgpr_read_b32 v6, a38
	v_accvgpr_read_b32 v7, a39
	v_accvgpr_read_b32 v8, a40
	v_accvgpr_read_b32 v9, a41
	v_accvgpr_read_b32 v10, a42
	v_accvgpr_read_b32 v11, a43
	v_accvgpr_read_b32 v12, a44
	v_accvgpr_read_b32 v13, a45
	v_accvgpr_read_b32 v14, a46
	v_accvgpr_read_b32 v15, a47
	v_div_fixup_f32 v172, v130, v131, 1.0
	s_barrier
	s_and_saveexec_b64 s[60:61], s[4:5]
	s_cbranch_execz .LBB0_1090
	v_accvgpr_read_b32 v133, a252
	v_mul_f32_e32 v130, v133, v224
	v_mul_f32_e32 v131, v112, v130
	v_mul_f32_e32 v132, v113, v130
	ds_write2st64_b32 v139, v131, v132 offset1:1
	v_mul_f32_e32 v131, v114, v130
	v_mul_f32_e32 v132, v115, v130
	ds_write2st64_b32 v139, v131, v132 offset0:2 offset1:3
	v_mul_f32_e32 v131, v116, v130
	v_mul_f32_e32 v132, v117, v130
	ds_write2st64_b32 v139, v131, v132 offset0:4 offset1:5
	v_mul_f32_e32 v131, v118, v130
	v_mul_f32_e32 v132, v119, v130
	ds_write2st64_b32 v139, v131, v132 offset0:6 offset1:7
	v_mul_f32_e32 v131, v120, v130
	v_mul_f32_e32 v132, v121, v130
	ds_write2st64_b32 v139, v131, v132 offset0:8 offset1:9
	v_mul_f32_e32 v131, v122, v130
	v_mul_f32_e32 v132, v123, v130
	ds_write2st64_b32 v139, v131, v132 offset0:10 offset1:11
	v_mul_f32_e32 v131, v124, v130
	v_mul_f32_e32 v132, v125, v130
	ds_write2st64_b32 v139, v131, v132 offset0:12 offset1:13
	v_mul_f32_e32 v131, v126, v130
	v_mul_f32_e32 v132, v127, v130
	ds_write2st64_b32 v139, v131, v132 offset0:14 offset1:15
	v_mul_f32_e32 v131, v96, v130
	v_mul_f32_e32 v132, v97, v130
	ds_write2st64_b32 v139, v131, v132 offset0:16 offset1:17
	v_mul_f32_e32 v131, v98, v130
	v_mul_f32_e32 v132, v99, v130
	ds_write2st64_b32 v139, v131, v132 offset0:18 offset1:19
	v_mul_f32_e32 v131, v100, v130
	v_mul_f32_e32 v132, v101, v130
	ds_write2st64_b32 v139, v131, v132 offset0:20 offset1:21
	v_mul_f32_e32 v131, v102, v130
	v_mul_f32_e32 v132, v103, v130
	ds_write2st64_b32 v139, v131, v132 offset0:22 offset1:23
	v_mul_f32_e32 v131, v104, v130
	v_mul_f32_e32 v132, v105, v130
	ds_write2st64_b32 v139, v131, v132 offset0:24 offset1:25
	v_mul_f32_e32 v131, v106, v130
	v_mul_f32_e32 v132, v107, v130
	ds_write2st64_b32 v139, v131, v132 offset0:26 offset1:27
	v_mul_f32_e32 v131, v108, v130
	v_mul_f32_e32 v132, v109, v130
	ds_write2st64_b32 v139, v131, v132 offset0:28 offset1:29
	v_mul_f32_e32 v131, v110, v130
	v_mul_f32_e32 v132, v111, v130
	ds_write2st64_b32 v139, v131, v132 offset0:30 offset1:31
	v_mul_f32_e32 v131, v80, v130
	v_mul_f32_e32 v132, v81, v130
	ds_write2st64_b32 v139, v131, v132 offset0:32 offset1:33
	v_mul_f32_e32 v131, v82, v130
	v_mul_f32_e32 v132, v83, v130
	ds_write2st64_b32 v139, v131, v132 offset0:34 offset1:35
	v_mul_f32_e32 v131, v84, v130
	v_mul_f32_e32 v132, v85, v130
	ds_write2st64_b32 v139, v131, v132 offset0:36 offset1:37
	v_mul_f32_e32 v131, v86, v130
	v_mul_f32_e32 v132, v87, v130
	ds_write2st64_b32 v139, v131, v132 offset0:38 offset1:39
	v_mul_f32_e32 v131, v88, v130
	v_mul_f32_e32 v132, v89, v130
	ds_write2st64_b32 v139, v131, v132 offset0:40 offset1:41
	v_mul_f32_e32 v131, v90, v130
	v_mul_f32_e32 v132, v91, v130
	ds_write2st64_b32 v139, v131, v132 offset0:42 offset1:43
	v_mul_f32_e32 v131, v92, v130
	v_mul_f32_e32 v132, v93, v130
	ds_write2st64_b32 v139, v131, v132 offset0:44 offset1:45
	v_mul_f32_e32 v131, v94, v130
	v_mul_f32_e32 v132, v95, v130
	ds_write2st64_b32 v139, v131, v132 offset0:46 offset1:47
	v_mul_f32_e32 v131, v64, v130
	v_mul_f32_e32 v132, v65, v130
	ds_write2st64_b32 v139, v131, v132 offset0:48 offset1:49
	v_mul_f32_e32 v131, v66, v130
	v_mul_f32_e32 v132, v67, v130
	ds_write2st64_b32 v139, v131, v132 offset0:50 offset1:51
	v_mul_f32_e32 v131, v68, v130
	v_mul_f32_e32 v132, v69, v130
	ds_write2st64_b32 v139, v131, v132 offset0:52 offset1:53
	v_mul_f32_e32 v131, v70, v130
	v_mul_f32_e32 v132, v71, v130
	ds_write2st64_b32 v139, v131, v132 offset0:54 offset1:55
	v_mul_f32_e32 v131, v72, v130
	v_mul_f32_e32 v132, v73, v130
	ds_write2st64_b32 v139, v131, v132 offset0:56 offset1:57
	v_mul_f32_e32 v131, v74, v130
	v_mul_f32_e32 v132, v75, v130
	ds_write2st64_b32 v139, v131, v132 offset0:58 offset1:59
	v_mul_f32_e32 v131, v76, v130
	v_mul_f32_e32 v132, v77, v130
	ds_write2st64_b32 v139, v131, v132 offset0:60 offset1:61
	v_mul_f32_e32 v131, v78, v130
	v_mul_f32_e32 v130, v79, v130
	ds_write2st64_b32 v139, v131, v130 offset0:62 offset1:63
	v_mul_f32_e32 v130, v133, v172
	v_mul_f32_e32 v131, v48, v130
	v_mul_f32_e32 v132, v49, v130
	ds_write2st64_b32 v254, v131, v132 offset1:1
	v_mul_f32_e32 v131, v50, v130
	v_mul_f32_e32 v132, v51, v130
	ds_write2st64_b32 v254, v131, v132 offset0:2 offset1:3
	v_mul_f32_e32 v131, v52, v130
	v_mul_f32_e32 v132, v53, v130
	ds_write2st64_b32 v254, v131, v132 offset0:4 offset1:5
	v_mul_f32_e32 v131, v54, v130
	v_mul_f32_e32 v132, v55, v130
	ds_write2st64_b32 v254, v131, v132 offset0:6 offset1:7
	v_mul_f32_e32 v131, v56, v130
	v_mul_f32_e32 v132, v57, v130
	ds_write2st64_b32 v254, v131, v132 offset0:8 offset1:9
	v_mul_f32_e32 v131, v58, v130
	v_mul_f32_e32 v132, v59, v130
	ds_write2st64_b32 v254, v131, v132 offset0:10 offset1:11
	v_mul_f32_e32 v131, v60, v130
	v_mul_f32_e32 v132, v61, v130
	ds_write2st64_b32 v254, v131, v132 offset0:12 offset1:13
	v_mul_f32_e32 v131, v62, v130
	v_mul_f32_e32 v132, v63, v130
	ds_write2st64_b32 v254, v131, v132 offset0:14 offset1:15
	v_mul_f32_e32 v131, v32, v130
	v_mul_f32_e32 v132, v33, v130
	ds_write2st64_b32 v254, v131, v132 offset0:16 offset1:17
	v_mul_f32_e32 v131, v34, v130
	v_mul_f32_e32 v132, v35, v130
	ds_write2st64_b32 v254, v131, v132 offset0:18 offset1:19
	v_mul_f32_e32 v131, v36, v130
	v_mul_f32_e32 v132, v37, v130
	ds_write2st64_b32 v254, v131, v132 offset0:20 offset1:21
	v_mul_f32_e32 v131, v38, v130
	v_mul_f32_e32 v132, v39, v130
	ds_write2st64_b32 v254, v131, v132 offset0:22 offset1:23
	v_mul_f32_e32 v131, v40, v130
	v_mul_f32_e32 v132, v41, v130
	ds_write2st64_b32 v254, v131, v132 offset0:24 offset1:25
	v_mul_f32_e32 v131, v42, v130
	v_mul_f32_e32 v132, v43, v130
	ds_write2st64_b32 v254, v131, v132 offset0:26 offset1:27
	v_mul_f32_e32 v131, v44, v130
	v_mul_f32_e32 v132, v45, v130
	ds_write2st64_b32 v254, v131, v132 offset0:28 offset1:29
	v_mul_f32_e32 v131, v46, v130
	v_mul_f32_e32 v132, v47, v130
	ds_write2st64_b32 v254, v131, v132 offset0:30 offset1:31
	v_mul_f32_e32 v131, v16, v130
	v_mul_f32_e32 v132, v17, v130
	ds_write2st64_b32 v254, v131, v132 offset0:32 offset1:33
	v_mul_f32_e32 v131, v18, v130
	v_mul_f32_e32 v132, v19, v130
	ds_write2st64_b32 v254, v131, v132 offset0:34 offset1:35
	v_mul_f32_e32 v131, v20, v130
	v_mul_f32_e32 v132, v21, v130
	ds_write2st64_b32 v254, v131, v132 offset0:36 offset1:37
	v_mul_f32_e32 v131, v22, v130
	v_mul_f32_e32 v132, v23, v130
	ds_write2st64_b32 v254, v131, v132 offset0:38 offset1:39
	v_mul_f32_e32 v131, v24, v130
	v_mul_f32_e32 v132, v25, v130
	ds_write2st64_b32 v254, v131, v132 offset0:40 offset1:41
	v_mul_f32_e32 v131, v26, v130
	v_mul_f32_e32 v132, v27, v130
	ds_write2st64_b32 v254, v131, v132 offset0:42 offset1:43
	v_mul_f32_e32 v131, v28, v130
	v_mul_f32_e32 v132, v29, v130
	ds_write2st64_b32 v254, v131, v132 offset0:44 offset1:45
	v_mul_f32_e32 v131, v30, v130
	v_mul_f32_e32 v132, v31, v130
	ds_write2st64_b32 v254, v131, v132 offset0:46 offset1:47
	v_mul_f32_e32 v131, v0, v130
	v_mul_f32_e32 v132, v1, v130
	ds_write2st64_b32 v254, v131, v132 offset0:48 offset1:49
	v_mul_f32_e32 v131, v2, v130
	v_mul_f32_e32 v132, v3, v130
	ds_write2st64_b32 v254, v131, v132 offset0:50 offset1:51
	v_mul_f32_e32 v131, v4, v130
	v_mul_f32_e32 v132, v5, v130
	ds_write2st64_b32 v254, v131, v132 offset0:52 offset1:53
	v_mul_f32_e32 v131, v6, v130
	v_mul_f32_e32 v132, v7, v130
	ds_write2st64_b32 v254, v131, v132 offset0:54 offset1:55
	v_mul_f32_e32 v131, v8, v130
	v_mul_f32_e32 v132, v9, v130
	ds_write2st64_b32 v254, v131, v132 offset0:56 offset1:57
	v_mul_f32_e32 v131, v10, v130
	v_mul_f32_e32 v132, v11, v130
	ds_write2st64_b32 v254, v131, v132 offset0:58 offset1:59
	v_mul_f32_e32 v131, v12, v130
	v_mul_f32_e32 v132, v13, v130
	ds_write2st64_b32 v254, v131, v132 offset0:60 offset1:61
	v_mul_f32_e32 v131, v14, v130
	v_mul_f32_e32 v130, v15, v130
	ds_write2st64_b32 v254, v131, v130 offset0:62 offset1:63

.LBB0_2270:
	s_lshl_b64 s[58:59], s[4:5], 10
	s_lshl_b64 s[64:65], s[4:5], 11
	v_mov_b32_e32 v243, v149
	s_lshl_b32 s4, s68, 7
	v_lshl_add_u64 v[0:1], s[62:63], 0, v[242:243]
	v_mov_b32_e32 v245, v149
	v_mov_b32_e32 v247, v149
	s_add_u32 s70, s62, s4
	v_lshl_add_u64 v[0:1], v[0:1], 0, v[244:245]
	v_lshl_add_u64 v[2:3], s[62:63], 0, v[246:247]
	s_addc_u32 s71, s63, 0
	v_lshl_add_u64 v[2:3], v[2:3], 0, v[244:245]
	global_load_dwordx4 v[32:35], v[0:1], off
	global_load_dwordx4 v[36:39], v[2:3], off
	v_lshl_add_u64 v[0:1], s[70:71], 0, v[242:243]
	v_lshl_add_u64 v[0:1], v[0:1], 0, v[244:245]
	v_lshl_add_u64 v[2:3], s[70:71], 0, v[246:247]
	v_lshl_add_u64 v[2:3], v[2:3], 0, v[244:245]
	global_load_dwordx4 v[40:43], v[0:1], off
	global_load_dwordx4 v[44:47], v[2:3], off
	v_accvgpr_read_b32 v0, a209
	v_mul_u32_u24_e32 v0, s68, v0
	v_lshlrev_b32_e32 v64, 1, v0
	v_mov_b32_e32 v65, v149
	v_mul_u32_u24_e32 v2, s68, v152
	v_lshl_add_u64 v[0:1], s[60:61], 0, v[64:65]
	v_lshlrev_b32_e32 v66, 1, v2
	v_mov_b32_e32 v67, v149
	v_lshl_add_u64 v[0:1], v[0:1], 0, v[244:245]
	v_lshl_add_u64 v[2:3], s[60:61], 0, v[66:67]
	v_lshl_add_u64 v[2:3], v[2:3], 0, v[244:245]
	global_load_dwordx4 v[48:51], v[0:1], off
	global_load_dwordx4 v[52:55], v[2:3], off
	v_mul_u32_u24_e32 v0, s68, v153
	v_lshlrev_b32_e32 v68, 1, v0
	v_mov_b32_e32 v69, v149
	v_mul_u32_u24_e32 v2, s68, v160
	v_lshl_add_u64 v[0:1], s[60:61], 0, v[68:69]
	v_lshlrev_b32_e32 v70, 1, v2
	v_mov_b32_e32 v71, v149
	v_lshl_add_u64 v[0:1], v[0:1], 0, v[244:245]
	v_lshl_add_u64 v[2:3], s[60:61], 0, v[70:71]
	v_lshl_add_u64 v[2:3], v[2:3], 0, v[244:245]
	global_load_dwordx4 v[56:59], v[0:1], off
	global_load_dwordx4 v[60:63], v[2:3], off
	v_mov_b32_e32 v251, v149
	v_lshl_add_u64 v[0:1], v[164:165], 0, s[64:65]
	v_lshl_add_u64 v[2:3], v[0:1], 0, v[148:149]
	v_lshl_add_u64 v[0:1], v[0:1], 0, v[250:251]
	global_load_dwordx4 v[28:31], v[2:3], off
	global_load_dwordx4 v[24:27], v[2:3], off offset:32
	global_load_dwordx4 v[20:23], v[2:3], off offset:64
	global_load_dwordx4 v[16:19], v[2:3], off offset:96
	global_load_dwordx4 v[12:15], v[0:1], off
	global_load_dwordx4 v[8:11], v[0:1], off offset:32
	global_load_dwordx4 v[4:7], v[0:1], off offset:64
	s_nop 0
	global_load_dwordx4 v[0:3], v[0:1], off offset:96
	v_lshl_add_u64 v[82:83], s[62:63], 0, v[146:147]
	v_lshl_add_u64 v[84:85], s[62:63], 0, v[166:167]
	v_lshl_add_u64 v[86:87], v[82:83], 0, s[4:5]
	v_lshl_add_u64 v[88:89], v[84:85], 0, s[4:5]
	s_add_i32 s4, s67, 1
	s_add_u32 s60, s60, 0x80
	v_mov_b32_e32 v80, 0
	s_addc_u32 s61, s61, 0
	v_accvgpr_write_b32 a31, 0
	v_accvgpr_write_b32 a30, 0
	v_accvgpr_write_b32 a29, 0
	v_accvgpr_write_b32 a28, 0
	v_accvgpr_write_b32 a27, 0
	v_accvgpr_write_b32 a26, 0
	v_accvgpr_write_b32 a25, 0
	v_accvgpr_write_b32 a24, 0
	v_accvgpr_write_b32 a23, 0
	v_accvgpr_write_b32 a22, 0
	v_lshl_add_u64 v[90:91], s[60:61], 0, v[64:65]
	v_lshl_add_u64 v[92:93], s[60:61], 0, v[66:67]
	v_lshl_add_u64 v[94:95], s[60:61], 0, v[68:69]
	v_lshl_add_u64 v[96:97], s[60:61], 0, v[70:71]
	v_accvgpr_write_b32 a21, 0
	v_accvgpr_write_b32 a20, 0
	v_accvgpr_write_b32 a19, 0
	v_accvgpr_write_b32 a18, 0
	v_accvgpr_write_b32 a17, 0
	v_accvgpr_write_b32 a16, 0
	v_accvgpr_write_b32 a111, 0
	v_accvgpr_write_b32 a110, 0
	v_accvgpr_write_b32 a109, 0
	v_accvgpr_write_b32 a108, 0
	v_accvgpr_write_b32 a107, 0
	v_accvgpr_write_b32 a106, 0
	v_accvgpr_write_b32 a105, 0
	v_accvgpr_write_b32 a104, 0
	v_accvgpr_write_b32 a103, 0
	v_accvgpr_write_b32 a102, 0
	v_accvgpr_write_b32 a101, 0
	v_accvgpr_write_b32 a100, 0
	v_accvgpr_write_b32 a99, 0
	v_accvgpr_write_b32 a98, 0
	v_accvgpr_write_b32 a97, 0
	v_accvgpr_write_b32 a96, 0
	v_accvgpr_write_b32 a143, 0
	v_accvgpr_write_b32 a142, 0
	v_accvgpr_write_b32 a141, 0
	v_accvgpr_write_b32 a140, 0
	v_accvgpr_write_b32 a139, 0
	v_accvgpr_write_b32 a138, 0
	v_accvgpr_write_b32 a137, 0
	v_accvgpr_write_b32 a136, 0
	v_accvgpr_write_b32 a135, 0
	v_accvgpr_write_b32 a134, 0
	v_accvgpr_write_b32 a133, 0
	v_accvgpr_write_b32 a132, 0
	v_accvgpr_write_b32 a131, 0
	v_accvgpr_write_b32 a130, 0
	v_accvgpr_write_b32 a129, 0
	v_accvgpr_write_b32 a128, 0
	v_accvgpr_write_b32 a63, 0
	v_accvgpr_write_b32 a62, 0
	v_accvgpr_write_b32 a61, 0
	v_accvgpr_write_b32 a60, 0
	v_accvgpr_write_b32 a59, 0
	v_accvgpr_write_b32 a58, 0
	v_accvgpr_write_b32 a57, 0
	v_accvgpr_write_b32 a56, 0
	v_accvgpr_write_b32 a55, 0
	v_accvgpr_write_b32 a54, 0
	v_accvgpr_write_b32 a53, 0
	v_accvgpr_write_b32 a52, 0
	v_accvgpr_write_b32 a51, 0
	v_accvgpr_write_b32 a50, 0
	v_accvgpr_write_b32 a49, 0
	v_accvgpr_write_b32 a48, 0
	v_accvgpr_write_b32 a95, 0
	v_accvgpr_write_b32 a94, 0
	v_accvgpr_write_b32 a93, 0
	v_accvgpr_write_b32 a92, 0
	v_accvgpr_write_b32 a91, 0
	v_accvgpr_write_b32 a90, 0
	v_accvgpr_write_b32 a89, 0
	v_accvgpr_write_b32 a88, 0
	v_accvgpr_write_b32 a87, 0
	v_accvgpr_write_b32 a86, 0
	v_accvgpr_write_b32 a85, 0
	v_accvgpr_write_b32 a84, 0
	v_accvgpr_write_b32 a83, 0
	v_accvgpr_write_b32 a82, 0
	v_accvgpr_write_b32 a81, 0
	v_accvgpr_write_b32 a80, 0
	v_accvgpr_write_b32 a47, 0
	v_accvgpr_write_b32 a46, 0
	v_accvgpr_write_b32 a45, 0
	v_accvgpr_write_b32 a44, 0
	v_accvgpr_write_b32 a43, 0
	v_accvgpr_write_b32 a42, 0
	v_accvgpr_write_b32 a41, 0
	v_accvgpr_write_b32 a40, 0
	v_accvgpr_write_b32 a39, 0
	v_accvgpr_write_b32 a38, 0
	v_accvgpr_write_b32 a37, 0
	v_accvgpr_write_b32 a36, 0
	v_accvgpr_write_b32 a35, 0
	v_accvgpr_write_b32 a34, 0
	v_accvgpr_write_b32 a33, 0
	v_accvgpr_write_b32 a32, 0
	v_accvgpr_write_b32 a127, 0
	v_accvgpr_write_b32 a126, 0
	v_accvgpr_write_b32 a125, 0
	v_accvgpr_write_b32 a124, 0
	v_accvgpr_write_b32 a123, 0
	v_accvgpr_write_b32 a122, 0
	v_accvgpr_write_b32 a121, 0
	v_accvgpr_write_b32 a120, 0
	v_accvgpr_write_b32 a119, 0
	v_accvgpr_write_b32 a118, 0
	v_accvgpr_write_b32 a117, 0
	v_accvgpr_write_b32 a116, 0
	v_accvgpr_write_b32 a115, 0
	v_accvgpr_write_b32 a114, 0
	v_accvgpr_write_b32 a113, 0
	v_accvgpr_write_b32 a112, 0
	v_accvgpr_write_b32 a79, 0
	v_accvgpr_write_b32 a78, 0
	v_accvgpr_write_b32 a77, 0
	v_accvgpr_write_b32 a76, 0
	v_accvgpr_write_b32 a75, 0
	v_accvgpr_write_b32 a74, 0
	v_accvgpr_write_b32 a73, 0
	v_accvgpr_write_b32 a72, 0
	v_accvgpr_write_b32 a71, 0
	v_accvgpr_write_b32 a70, 0
	v_accvgpr_write_b32 a69, 0
	v_accvgpr_write_b32 a68, 0
	v_accvgpr_write_b32 a67, 0
	v_accvgpr_write_b32 a66, 0
	v_accvgpr_write_b32 a65, 0
	v_accvgpr_write_b32 a64, 0
	s_mov_b32 s60, 0
	v_mov_b32_e32 v81, v80
	s_waitcnt vmcnt(15)
	ds_write_b128 v129, v[32:35]
	s_waitcnt vmcnt(14)
	ds_write_b128 v135, v[36:39]
	s_waitcnt vmcnt(13)
	ds_write_b128 v129, v[40:43] offset:9216
	s_waitcnt vmcnt(12)
	ds_write_b128 v135, v[44:47] offset:9216
	s_waitcnt vmcnt(11)
	ds_write_b128 v129, v[48:51] offset:36864
	s_waitcnt vmcnt(10)
	ds_write_b128 v135, v[52:55] offset:36864
	s_waitcnt vmcnt(9)
	ds_write_b128 v161, v[56:59] offset:36864
	s_waitcnt vmcnt(8)
	ds_write_b128 v162, v[60:63] offset:36864
	v_accvgpr_write_b32 a160, 0
	v_mov_b32_e32 v48, 0
	v_accvgpr_write_b32 a161, 0
	v_mov_b32_e32 v49, 0
	v_accvgpr_write_b32 a162, 0
	v_mov_b32_e32 v50, 0
	v_accvgpr_write_b32 a163, 0
	v_mov_b32_e32 v51, 0
	v_accvgpr_write_b32 a164, 0
	v_mov_b32_e32 v52, 0
	v_accvgpr_write_b32 a165, 0
	v_mov_b32_e32 v53, 0
	v_accvgpr_write_b32 a166, 0
	v_mov_b32_e32 v54, 0
	v_accvgpr_write_b32 a167, 0
	v_mov_b32_e32 v55, 0
	v_accvgpr_write_b32 a168, 0
	v_mov_b32_e32 v56, 0
	v_accvgpr_write_b32 a169, 0
	v_mov_b32_e32 v57, 0
	v_accvgpr_write_b32 a170, 0
	v_mov_b32_e32 v58, 0
	v_accvgpr_write_b32 a171, 0
	v_mov_b32_e32 v59, 0
	v_accvgpr_write_b32 a172, 0
	v_mov_b32_e32 v60, 0
	v_accvgpr_write_b32 a173, 0
	v_mov_b32_e32 v61, 0
	v_accvgpr_write_b32 a174, 0
	v_mov_b32_e32 v62, 0
	v_accvgpr_write_b32 a175, 0
	v_mov_b32_e32 v63, 0
	v_accvgpr_write_b32 a176, 0
	v_mov_b32_e32 v116, 0
	v_accvgpr_write_b32 a177, 0
	v_mov_b32_e32 v117, 0
	v_accvgpr_write_b32 a178, 0
	v_mov_b32_e32 v118, 0
	v_accvgpr_write_b32 a179, 0
	v_mov_b32_e32 v119, 0
	v_accvgpr_write_b32 a180, 0
	v_mov_b32_e32 v120, 0
	v_accvgpr_write_b32 a181, 0
	v_mov_b32_e32 v121, 0
	v_accvgpr_write_b32 a182, 0
	v_mov_b32_e32 v122, 0
	v_accvgpr_write_b32 a183, 0
	v_mov_b32_e32 v123, 0
	v_accvgpr_write_b32 a184, 0
	v_mov_b32_e32 v124, 0
	v_accvgpr_write_b32 a185, 0
	v_mov_b32_e32 v125, 0
	v_accvgpr_write_b32 a186, 0
	v_mov_b32_e32 v126, 0
	v_accvgpr_write_b32 a187, 0
	v_mov_b32_e32 v127, 0
	v_accvgpr_write_b32 a188, 0
	v_mov_b32_e32 v130, 0
	v_accvgpr_write_b32 a189, 0
	v_mov_b32_e32 v131, 0
	v_accvgpr_write_b32 a190, 0
	v_mov_b32_e32 v132, 0
	v_accvgpr_write_b32 a191, 0
	v_mov_b32_e32 v133, 0
	v_accvgpr_read_b32 v32, a0
	v_accvgpr_read_b32 v33, a0
	v_accvgpr_read_b32 v34, a0
	v_accvgpr_read_b32 v35, a0
	v_accvgpr_read_b32 v36, a0
	v_accvgpr_read_b32 v37, a0
	v_accvgpr_read_b32 v38, a0
	v_accvgpr_read_b32 v39, a0
	v_accvgpr_read_b32 v40, a0
	v_accvgpr_read_b32 v41, a0
	v_accvgpr_read_b32 v42, a0
	v_accvgpr_read_b32 v43, a0
	v_accvgpr_read_b32 v44, a0
	v_accvgpr_read_b32 v45, a0
	v_accvgpr_read_b32 v46, a0
	v_accvgpr_read_b32 v47, a0
	v_mbcnt_lo_u32_b32 v235, -1, 0
	v_mbcnt_hi_u32_b32 v235, -1, v235
	v_lshlrev_b32_e32 v235, 4, v235
	v_add_u32_e32 v235, 0xd800, v235
	s_waitcnt lgkmcnt(0)
	ds_write_b128 v235, a[160:163]
	ds_write_b128 v235, a[160:163] offset:1024
	ds_write_b128 v235, a[160:163] offset:2048
	ds_write_b128 v235, a[160:163] offset:3072
	ds_write_b128 v235, a[160:163] offset:4096
	ds_write_b128 v235, a[160:163] offset:5120
	ds_write_b128 v235, a[160:163] offset:6144
	ds_write_b128 v235, a[160:163] offset:7168
	ds_write_b128 v235, a[160:163] offset:8192
	s_waitcnt lgkmcnt(0)
	ds_write_b128 v235, a[160:163] offset:9216
	ds_write_b128 v235, a[160:163] offset:10240
	ds_write_b128 v235, a[160:163] offset:11264
	ds_write_b128 v235, a[160:163] offset:12288
	ds_write_b128 v235, a[160:163] offset:13312
	ds_write_b128 v235, a[160:163] offset:14336
	ds_write_b128 v235, a[160:163] offset:15360
	ds_write_b128 v235, a[160:163] offset:16384
	ds_write_b128 v235, a[160:163] offset:17408
	v_lshl_add_u64 v[98:99], v[82:83], 0, v[154:155]
	global_load_dwordx4 v[64:67], v[98:99], off
	v_lshl_add_u64 v[98:99], v[84:85], 0, v[154:155]
	global_load_dwordx4 v[68:71], v[98:99], off
	v_lshl_add_u64 v[98:99], v[86:87], 0, v[154:155]
	global_load_dwordx4 v[72:75], v[98:99], off
	v_lshl_add_u64 v[98:99], v[88:89], 0, v[154:155]
	global_load_dwordx4 v[76:79], v[98:99], off
	v_lshl_add_u64 v[82:83], v[82:83], 0, s[54:55]
	v_lshl_add_u64 v[84:85], v[84:85], 0, s[54:55]
	v_lshl_add_u64 v[86:87], v[86:87], 0, s[54:55]
	v_lshl_add_u64 v[88:89], v[88:89], 0, s[54:55]
.LBB0_2271:
	s_and_b32 s61, s60, 1
	s_xor_b32 s62, s61, 1
	s_mulk_i32 s61, 0x4800
	s_mulk_i32 s62, 0x4800
	v_add_u32_e32 v233, s61, v128
	v_add_u32_e32 v234, s62, v150
	s_waitcnt vmcnt(0) lgkmcnt(0)
	s_barrier
	ds_read_b128 a[144:147], v233
	ds_read_b128 a[148:151], v233 offset:32
	ds_read_b128 a[152:155], v233 offset:64
	ds_read_b128 a[156:159], v233 offset:96
	s_waitcnt lgkmcnt(3)
	v_mfma_f32_32x32x16_bf16 v[184:199], a[144:147], v[28:31], v[32:47]
	s_cmp_eq_u32 s60, 0
	s_cselect_b32 s32, 0x9000, s61
	v_add3_u32 v220, s32, v151, v134
	v_mfma_f32_32x32x16_bf16 v[168:183], a[144:147], v[12:15], v[32:47]
	v_add3_u32 v221, s32, v156, v134
	v_add3_u32 v222, s32, v157, v134
	v_add3_u32 v232, s32, v158, v134
	ds_read_b128 a[144:147], v233 offset:4608
	s_waitcnt lgkmcnt(3)
	v_mfma_f32_32x32x16_bf16 v[184:199], a[148:151], v[24:27], v[184:199]
	ds_write_b128 v220, v[140:143] offset:36864
	ds_write_b128 v221, v[216:219] offset:36864
	v_mfma_f32_32x32x16_bf16 v[168:183], a[148:151], v[8:11], v[168:183]
	ds_write_b128 v222, v[224:227] offset:36864
	ds_write_b128 v232, v[228:231] offset:36864
	v_accvgpr_write_b32 a160, v48
	ds_read_b128 a[148:151], v233 offset:4640
	s_waitcnt lgkmcnt(7)
	v_mfma_f32_32x32x16_bf16 v[184:199], a[152:155], v[20:23], v[184:199]
	v_accvgpr_write_b32 a161, v49
	v_accvgpr_write_b32 a162, v50
	v_accvgpr_write_b32 a163, v51
	v_mfma_f32_32x32x16_bf16 v[168:183], a[152:155], v[4:7], v[168:183]
	v_accvgpr_write_b32 a164, v52
	v_accvgpr_write_b32 a165, v53
	ds_read_b128 a[152:155], v233 offset:4672
	s_waitcnt lgkmcnt(7)
	v_mfma_f32_32x32x16_bf16 v[184:199], a[156:159], v[16:19], v[184:199]
	v_accvgpr_write_b32 a166, v54
	v_accvgpr_write_b32 a167, v55
	v_accvgpr_write_b32 a168, v56
	v_mfma_f32_32x32x16_bf16 v[168:183], a[156:159], v[0:3], v[168:183]
	v_accvgpr_write_b32 a169, v57
	v_accvgpr_write_b32 a170, v58
	ds_read_b128 a[156:159], v233 offset:4704
	s_waitcnt lgkmcnt(7)
	v_mfma_f32_32x32x16_bf16 v[200:215], a[144:147], v[28:31], v[32:47]
	v_accvgpr_write_b32 a171, v59
	v_accvgpr_write_b32 a172, v60
	v_accvgpr_write_b32 a173, v61
	v_mfma_f32_32x32x16_bf16 v[100:115], a[144:147], v[12:15], v[32:47]
	v_accvgpr_write_b32 a174, v62
	v_accvgpr_write_b32 a175, v63
	v_accvgpr_write_b32 a176, v116
	s_waitcnt lgkmcnt(2)
	v_mfma_f32_32x32x16_bf16 v[200:215], a[148:151], v[24:27], v[200:215]
	v_accvgpr_write_b32 a177, v117
	v_accvgpr_write_b32 a178, v118
	v_mfma_f32_32x32x16_bf16 v[100:115], a[148:151], v[8:11], v[100:115]
	v_accvgpr_write_b32 a179, v119
	v_accvgpr_write_b32 a180, v120
	v_accvgpr_write_b32 a181, v121
	s_waitcnt lgkmcnt(1)
	v_mfma_f32_32x32x16_bf16 v[200:215], a[152:155], v[20:23], v[200:215]
	v_accvgpr_write_b32 a182, v122
	v_accvgpr_write_b32 a183, v123
	v_accvgpr_write_b32 a184, v124
	v_mfma_f32_32x32x16_bf16 v[100:115], a[152:155], v[4:7], v[100:115]
	v_accvgpr_write_b32 a185, v125
	v_accvgpr_write_b32 a186, v126
	s_waitcnt lgkmcnt(0)
	v_mfma_f32_32x32x16_bf16 v[200:215], a[156:159], v[16:19], v[200:215]
	v_accvgpr_write_b32 a187, v127
	v_accvgpr_write_b32 a188, v130
	v_accvgpr_write_b32 a189, v131
	v_mfma_f32_32x32x16_bf16 v[100:115], a[156:159], v[0:3], v[100:115]
	v_accvgpr_write_b32 a190, v132
	v_accvgpr_write_b32 a191, v133
	ds_read_b128 a[144:147], v234 offset:36864
	ds_read_b128 a[148:151], v234 offset:36896
	ds_read_b128 a[152:155], v234 offset:36928
	ds_read_b128 a[156:159], v234 offset:36960
	s_waitcnt lgkmcnt(3)
	v_mfma_f32_32x32x16_bf16 a[128:143], a[144:147], a[160:163], a[128:143]
	v_exp_f32_e32 v184, v184
	v_exp_f32_e32 v185, v185
	v_exp_f32_e32 v186, v186
	v_exp_f32_e32 v187, v187
	v_mfma_f32_32x32x16_bf16 a[112:127], a[144:147], a[176:179], a[112:127]
	v_exp_f32_e32 v188, v188
	v_exp_f32_e32 v189, v189
	v_exp_f32_e32 v190, v190
	v_exp_f32_e32 v191, v191
	ds_read_b128 a[144:147], v234 offset:41472
	s_waitcnt lgkmcnt(3)
	v_mfma_f32_32x32x16_bf16 a[128:143], a[148:151], a[164:167], a[128:143]
	v_exp_f32_e32 v192, v192
	v_exp_f32_e32 v193, v193
	v_exp_f32_e32 v194, v194
	v_exp_f32_e32 v195, v195
	v_mfma_f32_32x32x16_bf16 a[112:127], a[148:151], a[180:183], a[112:127]
	v_exp_f32_e32 v196, v196
	v_exp_f32_e32 v197, v197
	v_exp_f32_e32 v198, v198
	v_exp_f32_e32 v199, v199
	ds_read_b128 a[148:151], v234 offset:41504
	s_waitcnt lgkmcnt(3)
	v_mfma_f32_32x32x16_bf16 a[128:143], a[152:155], a[168:171], a[128:143]
	v_pk_add_f32 v[136:137], v[184:185], v[186:187]
	v_pk_add_f32 v[136:137], v[136:137], v[188:189]
	v_pk_add_f32 v[136:137], v[136:137], v[190:191]
	v_pk_add_f32 v[136:137], v[136:137], v[192:193]
	v_mfma_f32_32x32x16_bf16 a[112:127], a[152:155], a[184:187], a[112:127]
	v_pk_add_f32 v[136:137], v[136:137], v[194:195]
	v_pk_add_f32 v[136:137], v[136:137], v[196:197]
	v_pk_add_f32 v[136:137], v[136:137], v[198:199]
	v_cvt_pk_bf16_f32 v48, v184, v185
	v_cvt_pk_bf16_f32 v49, v186, v187
	ds_read_b128 a[152:155], v234 offset:41536
	s_waitcnt lgkmcnt(3)
	v_mfma_f32_32x32x16_bf16 a[128:143], a[156:159], a[172:175], a[128:143]
	v_cvt_pk_bf16_f32 v50, v188, v189
	v_cvt_pk_bf16_f32 v51, v190, v191
	v_cvt_pk_bf16_f32 v52, v192, v193
	v_cvt_pk_bf16_f32 v53, v194, v195
	v_cvt_pk_bf16_f32 v54, v196, v197
	v_cvt_pk_bf16_f32 v55, v198, v199
	v_add3_u32 v220, s62, v151, v134
	v_add3_u32 v221, s62, v156, v134
	s_waitcnt vmcnt(3)
	v_mfma_f32_32x32x16_bf16 a[112:127], a[156:159], a[188:191], a[112:127]
	ds_write_b128 v220, v[64:67]
	s_waitcnt vmcnt(2)
	ds_write_b128 v221, v[68:71]
	s_waitcnt vmcnt(1)
	ds_write_b128 v220, v[72:75] offset:9216
	s_waitcnt vmcnt(0)
	ds_write_b128 v221, v[76:79] offset:9216
	ds_read_b128 a[156:159], v234 offset:41568
	s_waitcnt lgkmcnt(7)
	v_mfma_f32_32x32x16_bf16 a[48:63], a[144:147], a[160:163], a[48:63]
	v_lshl_add_u64 v[98:99], v[82:83], 0, v[154:155]
	global_load_dwordx4 v[64:67], v[98:99], off
	v_lshl_add_u64 v[98:99], v[84:85], 0, v[154:155]
	global_load_dwordx4 v[68:71], v[98:99], off
	v_lshl_add_u64 v[98:99], v[86:87], 0, v[154:155]
	global_load_dwordx4 v[72:75], v[98:99], off
	v_lshl_add_u64 v[98:99], v[88:89], 0, v[154:155]
	global_load_dwordx4 v[76:79], v[98:99], off
	v_mfma_f32_32x32x16_bf16 a[64:79], a[144:147], a[176:179], a[64:79]
	v_lshl_add_u64 v[82:83], v[82:83], 0, s[54:55]
	v_lshl_add_u64 v[84:85], v[84:85], 0, s[54:55]
	v_lshl_add_u64 v[86:87], v[86:87], 0, s[54:55]
	v_lshl_add_u64 v[88:89], v[88:89], 0, s[54:55]
	v_lshl_add_u64 v[98:99], v[90:91], 0, v[154:155]
	global_load_dwordx4 v[140:143], v[98:99], off
	v_lshl_add_u64 v[98:99], v[92:93], 0, v[154:155]
	global_load_dwordx4 v[216:219], v[98:99], off
	ds_read_b128 a[144:147], v234 offset:46080
	s_waitcnt lgkmcnt(7)
	v_mfma_f32_32x32x16_bf16 a[48:63], a[148:151], a[164:167], a[48:63]
	v_lshl_add_u64 v[98:99], v[94:95], 0, v[154:155]
	global_load_dwordx4 v[224:227], v[98:99], off
	v_lshl_add_u64 v[98:99], v[96:97], 0, v[154:155]
	global_load_dwordx4 v[228:231], v[98:99], off
	v_lshl_add_u64 v[90:91], v[90:91], 0, s[56:57]
	v_lshl_add_u64 v[92:93], v[92:93], 0, s[56:57]
	v_lshl_add_u64 v[94:95], v[94:95], 0, s[56:57]
	v_lshl_add_u64 v[96:97], v[96:97], 0, s[56:57]
	v_mfma_f32_32x32x16_bf16 a[64:79], a[148:151], a[180:183], a[64:79]
	v_exp_f32_e32 v168, v168
	v_exp_f32_e32 v169, v169
	v_exp_f32_e32 v170, v170
	v_exp_f32_e32 v171, v171
	ds_read_b128 a[148:151], v234 offset:46112
	s_waitcnt lgkmcnt(7)
	v_mfma_f32_32x32x16_bf16 a[48:63], a[152:155], a[168:171], a[48:63]
	v_exp_f32_e32 v172, v172
	v_exp_f32_e32 v173, v173
	v_exp_f32_e32 v174, v174
	v_exp_f32_e32 v175, v175
	v_mfma_f32_32x32x16_bf16 a[64:79], a[152:155], a[184:187], a[64:79]
	v_exp_f32_e32 v176, v176
	v_exp_f32_e32 v177, v177
	v_exp_f32_e32 v178, v178
	v_exp_f32_e32 v179, v179
	ds_read_b128 a[152:155], v234 offset:46144
	s_waitcnt lgkmcnt(3)
	v_mfma_f32_32x32x16_bf16 a[48:63], a[156:159], a[172:175], a[48:63]
	v_exp_f32_e32 v180, v180
	v_exp_f32_e32 v181, v181
	v_exp_f32_e32 v182, v182
	v_exp_f32_e32 v183, v183
	v_mfma_f32_32x32x16_bf16 a[64:79], a[156:159], a[188:191], a[64:79]
	v_pk_add_f32 v[144:145], v[168:169], v[170:171]
	v_pk_add_f32 v[144:145], v[144:145], v[172:173]
	v_pk_add_f32 v[144:145], v[144:145], v[174:175]
	v_pk_add_f32 v[144:145], v[144:145], v[176:177]
	ds_read_b128 a[156:159], v234 offset:46176
	s_waitcnt lgkmcnt(3)
	v_mfma_f32_32x32x16_bf16 a[80:95], a[144:147], a[160:163], a[80:95]
	v_pk_add_f32 v[144:145], v[144:145], v[178:179]
	v_pk_add_f32 v[144:145], v[144:145], v[180:181]
	v_pk_add_f32 v[144:145], v[144:145], v[182:183]
	v_cvt_pk_bf16_f32 v116, v168, v169
	v_cvt_pk_bf16_f32 v117, v170, v171
	v_cvt_pk_bf16_f32 v118, v172, v173
	v_mfma_f32_32x32x16_bf16 a[96:111], a[144:147], a[176:179], a[96:111]
	v_cvt_pk_bf16_f32 v119, v174, v175
	v_cvt_pk_bf16_f32 v120, v176, v177
	v_cvt_pk_bf16_f32 v121, v178, v179
	v_cvt_pk_bf16_f32 v122, v180, v181
	v_cvt_pk_bf16_f32 v123, v182, v183
	v_exp_f32_e32 v200, v200
	ds_read_b128 a[144:147], v234 offset:50688
	s_waitcnt lgkmcnt(3)
	v_mfma_f32_32x32x16_bf16 a[80:95], a[148:151], a[164:167], a[80:95]
	v_exp_f32_e32 v201, v201
	v_exp_f32_e32 v202, v202
	v_exp_f32_e32 v203, v203
	v_exp_f32_e32 v204, v204
	v_mfma_f32_32x32x16_bf16 a[96:111], a[148:151], a[180:183], a[96:111]
	v_exp_f32_e32 v205, v205
	v_exp_f32_e32 v206, v206
	v_exp_f32_e32 v207, v207
	v_exp_f32_e32 v208, v208
	ds_read_b128 a[148:151], v234 offset:50720
	s_waitcnt lgkmcnt(3)
	v_mfma_f32_32x32x16_bf16 a[80:95], a[152:155], a[168:171], a[80:95]
	v_exp_f32_e32 v209, v209
	v_exp_f32_e32 v210, v210
	v_exp_f32_e32 v211, v211
	v_exp_f32_e32 v212, v212
	v_mfma_f32_32x32x16_bf16 a[96:111], a[152:155], a[184:187], a[96:111]
	v_exp_f32_e32 v213, v213
	v_exp_f32_e32 v214, v214
	v_exp_f32_e32 v215, v215
	v_pk_add_f32 v[136:137], v[136:137], v[200:201]
	ds_read_b128 a[152:155], v234 offset:50752
	s_waitcnt lgkmcnt(3)
	v_mfma_f32_32x32x16_bf16 a[80:95], a[156:159], a[172:175], a[80:95]
	v_pk_add_f32 v[136:137], v[136:137], v[202:203]
	v_pk_add_f32 v[136:137], v[136:137], v[204:205]
	v_pk_add_f32 v[136:137], v[136:137], v[206:207]
	v_pk_add_f32 v[136:137], v[136:137], v[208:209]
	v_mfma_f32_32x32x16_bf16 a[96:111], a[156:159], a[188:191], a[96:111]
	v_pk_add_f32 v[136:137], v[136:137], v[210:211]
	v_pk_add_f32 v[136:137], v[136:137], v[212:213]
	v_pk_add_f32 v[136:137], v[136:137], v[214:215]
	v_cvt_pk_bf16_f32 v56, v200, v201
	v_cvt_pk_bf16_f32 v57, v202, v203
	v_cvt_pk_bf16_f32 v58, v204, v205
	ds_read_b128 a[156:159], v234 offset:50784
	s_waitcnt lgkmcnt(3)
	v_mfma_f32_32x32x16_bf16 a[32:47], a[144:147], a[160:163], a[32:47]
	v_cvt_pk_bf16_f32 v59, v206, v207
	v_cvt_pk_bf16_f32 v60, v208, v209
	v_cvt_pk_bf16_f32 v61, v210, v211
	v_cvt_pk_bf16_f32 v62, v212, v213
	v_cvt_pk_bf16_f32 v63, v214, v215
	v_add_f32_e32 v235, v136, v137
	v_add_f32_e32 v81, v81, v235
	v_mfma_f32_32x32x16_bf16 a[16:31], a[144:147], a[176:179], a[16:31]
	v_exp_f32_e32 v100, v100
	v_exp_f32_e32 v101, v101
	v_exp_f32_e32 v102, v102
	v_exp_f32_e32 v103, v103
	s_waitcnt lgkmcnt(2)
	v_mfma_f32_32x32x16_bf16 a[32:47], a[148:151], a[164:167], a[32:47]
	v_exp_f32_e32 v104, v104
	v_exp_f32_e32 v105, v105
	v_exp_f32_e32 v106, v106
	v_exp_f32_e32 v107, v107
	v_mfma_f32_32x32x16_bf16 a[16:31], a[148:151], a[180:183], a[16:31]
	v_exp_f32_e32 v108, v108
	v_exp_f32_e32 v109, v109
	v_exp_f32_e32 v110, v110
	v_exp_f32_e32 v111, v111
	s_waitcnt lgkmcnt(1)
	v_mfma_f32_32x32x16_bf16 a[32:47], a[152:155], a[168:171], a[32:47]
	v_exp_f32_e32 v112, v112
	v_exp_f32_e32 v113, v113
	v_exp_f32_e32 v114, v114
	v_exp_f32_e32 v115, v115
	v_mfma_f32_32x32x16_bf16 a[16:31], a[152:155], a[184:187], a[16:31]
	v_pk_add_f32 v[144:145], v[144:145], v[100:101]
	v_pk_add_f32 v[144:145], v[144:145], v[102:103]
	v_pk_add_f32 v[144:145], v[144:145], v[104:105]
	v_pk_add_f32 v[144:145], v[144:145], v[106:107]
	s_waitcnt lgkmcnt(0)
	v_mfma_f32_32x32x16_bf16 a[32:47], a[156:159], a[172:175], a[32:47]
	v_pk_add_f32 v[144:145], v[144:145], v[108:109]
	v_pk_add_f32 v[144:145], v[144:145], v[110:111]
	v_pk_add_f32 v[144:145], v[144:145], v[112:113]
	v_pk_add_f32 v[144:145], v[144:145], v[114:115]
	v_cvt_pk_bf16_f32 v124, v100, v101
	v_mfma_f32_32x32x16_bf16 a[16:31], a[156:159], a[188:191], a[16:31]
	v_cvt_pk_bf16_f32 v125, v102, v103
	v_cvt_pk_bf16_f32 v126, v104, v105
	v_cvt_pk_bf16_f32 v127, v106, v107
	v_cvt_pk_bf16_f32 v130, v108, v109
	v_cvt_pk_bf16_f32 v131, v110, v111
	v_cvt_pk_bf16_f32 v132, v112, v113
	v_cvt_pk_bf16_f32 v133, v114, v115
	v_add_f32_e32 v235, v144, v145
	v_add_f32_e32 v80, v80, v235
	s_add_i32 s60, s60, 1
	s_cmp_eq_u32 s4, s60
	s_cbranch_scc0 .LBB0_2271
	s_waitcnt vmcnt(0) lgkmcnt(0)
	s_barrier
	v_add3_u32 v220, s62, v151, v134
	v_add3_u32 v221, s62, v156, v134
	v_add3_u32 v222, s62, v157, v134
	v_add3_u32 v232, s62, v158, v134
	ds_write_b128 v220, v[140:143] offset:36864
	ds_write_b128 v221, v[216:219] offset:36864
	ds_write_b128 v222, v[224:227] offset:36864
	ds_write_b128 v232, v[228:231] offset:36864
	v_add_u32_e32 v234, s61, v150
	ds_read_b128 a[144:147], v234 offset:36864
	ds_read_b128 a[148:151], v234 offset:36896
	ds_read_b128 a[152:155], v234 offset:36928
	ds_read_b128 a[156:159], v234 offset:36960
	s_waitcnt lgkmcnt(3)
	v_mfma_f32_32x32x16_bf16 a[128:143], a[144:147], v[48:51], a[128:143]
	v_mfma_f32_32x32x16_bf16 a[112:127], a[144:147], v[116:119], a[112:127]
	ds_read_b128 a[144:147], v234 offset:41472
	s_waitcnt lgkmcnt(3)
	v_mfma_f32_32x32x16_bf16 a[128:143], a[148:151], v[52:55], a[128:143]
	v_mfma_f32_32x32x16_bf16 a[112:127], a[148:151], v[120:123], a[112:127]
	ds_read_b128 a[148:151], v234 offset:41504
	s_waitcnt lgkmcnt(3)
	v_mfma_f32_32x32x16_bf16 a[128:143], a[152:155], v[56:59], a[128:143]
	v_mfma_f32_32x32x16_bf16 a[112:127], a[152:155], v[124:127], a[112:127]
	ds_read_b128 a[152:155], v234 offset:41536
	s_waitcnt lgkmcnt(3)
	v_mfma_f32_32x32x16_bf16 a[128:143], a[156:159], v[60:63], a[128:143]
	v_mfma_f32_32x32x16_bf16 a[112:127], a[156:159], v[130:133], a[112:127]
	ds_read_b128 a[156:159], v234 offset:41568
	s_waitcnt lgkmcnt(3)
	v_mfma_f32_32x32x16_bf16 a[48:63], a[144:147], v[48:51], a[48:63]
	v_mfma_f32_32x32x16_bf16 a[64:79], a[144:147], v[116:119], a[64:79]
	ds_read_b128 a[144:147], v234 offset:46080
	s_waitcnt lgkmcnt(3)
	v_mfma_f32_32x32x16_bf16 a[48:63], a[148:151], v[52:55], a[48:63]
	v_mfma_f32_32x32x16_bf16 a[64:79], a[148:151], v[120:123], a[64:79]
	ds_read_b128 a[148:151], v234 offset:46112
	s_waitcnt lgkmcnt(3)
	v_mfma_f32_32x32x16_bf16 a[48:63], a[152:155], v[56:59], a[48:63]
	v_mfma_f32_32x32x16_bf16 a[64:79], a[152:155], v[124:127], a[64:79]
	ds_read_b128 a[152:155], v234 offset:46144
	s_waitcnt lgkmcnt(3)
	v_mfma_f32_32x32x16_bf16 a[48:63], a[156:159], v[60:63], a[48:63]
	v_mfma_f32_32x32x16_bf16 a[64:79], a[156:159], v[130:133], a[64:79]
	ds_read_b128 a[156:159], v234 offset:46176
	s_waitcnt lgkmcnt(3)
	v_mfma_f32_32x32x16_bf16 a[80:95], a[144:147], v[48:51], a[80:95]
	v_mfma_f32_32x32x16_bf16 a[96:111], a[144:147], v[116:119], a[96:111]
	ds_read_b128 a[144:147], v234 offset:50688
	s_waitcnt lgkmcnt(3)
	v_mfma_f32_32x32x16_bf16 a[80:95], a[148:151], v[52:55], a[80:95]
	v_mfma_f32_32x32x16_bf16 a[96:111], a[148:151], v[120:123], a[96:111]
	ds_read_b128 a[148:151], v234 offset:50720
	s_waitcnt lgkmcnt(3)
	v_mfma_f32_32x32x16_bf16 a[80:95], a[152:155], v[56:59], a[80:95]
	v_mfma_f32_32x32x16_bf16 a[96:111], a[152:155], v[124:127], a[96:111]
	ds_read_b128 a[152:155], v234 offset:50752
	s_waitcnt lgkmcnt(3)
	v_mfma_f32_32x32x16_bf16 a[80:95], a[156:159], v[60:63], a[80:95]
	v_mfma_f32_32x32x16_bf16 a[96:111], a[156:159], v[130:133], a[96:111]
	ds_read_b128 a[156:159], v234 offset:50784
	s_waitcnt lgkmcnt(3)
	v_mfma_f32_32x32x16_bf16 a[32:47], a[144:147], v[48:51], a[32:47]
	v_mfma_f32_32x32x16_bf16 a[16:31], a[144:147], v[116:119], a[16:31]
	s_waitcnt lgkmcnt(2)
	v_mfma_f32_32x32x16_bf16 a[32:47], a[148:151], v[52:55], a[32:47]
	v_mfma_f32_32x32x16_bf16 a[16:31], a[148:151], v[120:123], a[16:31]
	s_waitcnt lgkmcnt(1)
	v_mfma_f32_32x32x16_bf16 a[32:47], a[152:155], v[56:59], a[32:47]
	v_mfma_f32_32x32x16_bf16 a[16:31], a[152:155], v[124:127], a[16:31]
	s_waitcnt lgkmcnt(0)
	v_mfma_f32_32x32x16_bf16 a[32:47], a[156:159], v[60:63], a[32:47]
	v_mfma_f32_32x32x16_bf16 a[16:31], a[156:159], v[130:133], a[16:31]
	s_bitcmp1_b32 s4, 0
	s_cselect_b32 s4, 0x4800, 0
	v_add_u32_e32 v48, s4, v128
	s_waitcnt lgkmcnt(0)
	s_barrier
	ds_read_b128 v[32:35], v48
	ds_read_b128 v[36:39], v48 offset:32
	s_waitcnt lgkmcnt(1)
	v_mfma_f32_32x32x16_bf16 a[186:201], v[32:35], v[28:31], a[0:15]
	v_add_u32_e32 v83, s4, v150
	v_mfma_f32_32x32x16_bf16 a[144:159], v[32:35], v[12:15], a[0:15]
	s_waitcnt lgkmcnt(0)
	v_mfma_f32_32x32x16_bf16 a[186:201], v[36:39], v[24:27], a[186:201]
	v_mfma_f32_32x32x16_bf16 a[144:159], v[36:39], v[8:11], a[144:159]
	ds_read_b128 v[32:35], v48 offset:64
	ds_read_b128 v[36:39], v48 offset:96
	s_waitcnt lgkmcnt(1)
	v_mfma_f32_32x32x16_bf16 a[186:201], v[32:35], v[20:23], a[186:201]
	s_waitcnt lgkmcnt(0)
	v_mfma_f32_32x32x16_bf16 a[186:201], v[36:39], v[16:19], a[186:201]
	v_mfma_f32_32x32x16_bf16 a[144:159], v[32:35], v[4:7], a[144:159]
	ds_read_b128 v[32:35], v48 offset:4608
	ds_read_b128 v[40:43], v48 offset:4640
	ds_read_b128 v[44:47], v48 offset:4672
	ds_read_b128 v[48:51], v48 offset:4704
	s_nop 6
	v_accvgpr_read_b32 v52, a186
	v_accvgpr_read_b32 v53, a187
	v_accvgpr_read_b32 v54, a188
	v_exp_f32_e32 v52, v52
	v_exp_f32_e32 v53, v53
	s_waitcnt lgkmcnt(3)
	v_mfma_f32_32x32x16_bf16 a[172:187], v[32:35], v[28:31], a[0:15]
	v_accvgpr_read_b32 v28, a189
	v_exp_f32_e32 v55, v28
	v_accvgpr_read_b32 v28, a190
	v_exp_f32_e32 v56, v28
	v_accvgpr_read_b32 v28, a191
	v_exp_f32_e32 v54, v54
	v_exp_f32_e32 v57, v28
	s_waitcnt lgkmcnt(2)
	v_mfma_f32_32x32x16_bf16 a[172:187], v[40:43], v[24:27], a[172:187]
	v_accvgpr_read_b32 v24, a192
	v_exp_f32_e32 v58, v24
	v_accvgpr_read_b32 v24, a193
	v_exp_f32_e32 v59, v24
	v_accvgpr_read_b32 v24, a194
	v_exp_f32_e32 v60, v24
	v_accvgpr_read_b32 v24, a195
	s_waitcnt lgkmcnt(1)
	v_mfma_f32_32x32x16_bf16 a[172:187], v[44:47], v[20:23], a[172:187]
	v_accvgpr_read_b32 v20, a196
	v_exp_f32_e32 v62, v20
	v_accvgpr_read_b32 v20, a197
	v_exp_f32_e32 v63, v20
	v_accvgpr_read_b32 v20, a198
	v_exp_f32_e32 v64, v20
	v_exp_f32_e32 v61, v24
	s_waitcnt lgkmcnt(0)
	v_mfma_f32_32x32x16_bf16 a[172:187], v[48:51], v[16:19], a[172:187]
	v_accvgpr_read_b32 v16, a199
	v_exp_f32_e32 v65, v16
	v_accvgpr_read_b32 v16, a200
	v_exp_f32_e32 v66, v16
	v_accvgpr_read_b32 v16, a201
	v_exp_f32_e32 v67, v16
	ds_read_b128 v[28:31], v83 offset:36928
	v_mfma_f32_32x32x16_bf16 a[144:159], v[36:39], v[0:3], a[144:159]
	s_nop 3
	v_accvgpr_read_b32 v16, a172
	v_exp_f32_e32 v36, v16
	v_accvgpr_read_b32 v16, a173
	v_exp_f32_e32 v37, v16
	v_accvgpr_read_b32 v16, a174
	v_exp_f32_e32 v38, v16
	v_accvgpr_read_b32 v16, a175
	v_mfma_f32_32x32x16_bf16 a[160:175], v[32:35], v[12:15], a[0:15]
	v_exp_f32_e32 v39, v16
	v_accvgpr_read_b32 v16, a144
	v_accvgpr_read_b32 v12, a176
	v_exp_f32_e32 v68, v12
	v_accvgpr_read_b32 v12, a177
	v_accvgpr_read_b32 v20, a157
	v_exp_f32_e32 v69, v12
	v_mfma_f32_32x32x16_bf16 a[160:175], v[40:43], v[8:11], a[160:175]
	v_accvgpr_read_b32 v12, a178
	v_exp_f32_e32 v84, v20
	v_accvgpr_read_b32 v20, a158
	v_exp_f32_e32 v70, v12
	v_accvgpr_read_b32 v12, a179
	v_exp_f32_e32 v85, v20
	v_accvgpr_read_b32 v20, a159
	v_mfma_f32_32x32x16_bf16 a[160:175], v[44:47], v[4:7], a[160:175]
	v_exp_f32_e32 v40, v12
	v_cvt_pk_bf16_f32 v12, v52, v53
	v_cvt_pk_bf16_f32 v13, v54, v55
	v_cvt_pk_bf16_f32 v14, v56, v57
	v_cvt_pk_bf16_f32 v15, v58, v59
	v_exp_f32_e32 v86, v20
	ds_read_b128 v[20:23], v83 offset:36896
	v_mfma_f32_32x32x16_bf16 a[160:175], v[48:51], v[0:3], a[160:175]
	v_exp_f32_e32 v49, v16
	v_accvgpr_read_b32 v16, a145
	v_exp_f32_e32 v50, v16
	v_accvgpr_read_b32 v16, a146
	v_exp_f32_e32 v51, v16
	v_accvgpr_read_b32 v16, a147
	v_exp_f32_e32 v71, v16
	v_accvgpr_read_b32 v16, a148
	v_exp_f32_e32 v72, v16
	v_accvgpr_read_b32 v16, a149
	v_exp_f32_e32 v73, v16
	v_accvgpr_read_b32 v16, a150
	v_exp_f32_e32 v74, v16
	v_accvgpr_read_b32 v16, a151
	v_exp_f32_e32 v75, v16
	v_accvgpr_read_b32 v16, a152
	v_exp_f32_e32 v76, v16
	v_accvgpr_read_b32 v16, a153
	v_exp_f32_e32 v77, v16
	v_accvgpr_read_b32 v16, a154
	v_exp_f32_e32 v78, v16
	v_accvgpr_read_b32 v16, a155
	v_exp_f32_e32 v79, v16
	v_accvgpr_read_b32 v16, a156
	v_exp_f32_e32 v82, v16
	ds_read_b128 v[16:19], v83 offset:36864
	v_accvgpr_read_b32 v24, a160
	v_exp_f32_e32 v87, v24
	v_accvgpr_read_b32 v24, a161
	v_exp_f32_e32 v88, v24
	v_cvt_pk_bf16_f32 v24, v49, v50
	v_cvt_pk_bf16_f32 v25, v51, v71
	v_cvt_pk_bf16_f32 v26, v72, v73
	v_cvt_pk_bf16_f32 v27, v74, v75
	s_waitcnt lgkmcnt(0)
	v_mfma_f32_32x32x16_bf16 a[144:159], v[16:19], v[12:15], a[128:143]
	v_accvgpr_read_b32 v8, a180
	v_exp_f32_e32 v41, v8
	v_accvgpr_read_b32 v8, a181
	v_exp_f32_e32 v42, v8
	v_accvgpr_read_b32 v8, a182
	v_exp_f32_e32 v43, v8
	v_cvt_pk_bf16_f32 v8, v60, v61
	v_mfma_f32_32x32x16_bf16 a[128:143], v[16:19], v[24:27], a[112:127]
	v_accvgpr_read_b32 v16, a162
	v_exp_f32_e32 v89, v16
	v_accvgpr_read_b32 v16, a163
	v_exp_f32_e32 v90, v16
	v_accvgpr_read_b32 v16, a164
	v_exp_f32_e32 v91, v16
	v_accvgpr_read_b32 v16, a165
	v_cvt_pk_bf16_f32 v9, v62, v63
	v_cvt_pk_bf16_f32 v10, v64, v65
	v_cvt_pk_bf16_f32 v11, v66, v67
	v_exp_f32_e32 v92, v16
	v_cvt_pk_bf16_f32 v16, v76, v77
	v_cvt_pk_bf16_f32 v17, v78, v79
	v_cvt_pk_bf16_f32 v18, v82, v84
	v_cvt_pk_bf16_f32 v19, v85, v86
	v_mfma_f32_32x32x16_bf16 a[144:159], v[20:23], v[8:11], a[144:159]
	v_accvgpr_read_b32 v32, a166
	v_accvgpr_read_b32 v4, a183
	v_exp_f32_e32 v93, v32
	v_exp_f32_e32 v44, v4
	v_accvgpr_read_b32 v4, a184
	v_exp_f32_e32 v45, v4
	v_accvgpr_read_b32 v4, a185
	v_mfma_f32_32x32x16_bf16 a[128:143], v[20:23], v[16:19], a[128:143]
	v_accvgpr_read_b32 v20, a167
	v_exp_f32_e32 v94, v20
	v_accvgpr_read_b32 v32, a169
	v_exp_f32_e32 v46, v4
	v_accvgpr_read_b32 v4, a186
	v_exp_f32_e32 v96, v32
	v_accvgpr_read_b32 v32, a170
	v_exp_f32_e32 v47, v4
	v_cvt_pk_bf16_f32 v4, v36, v37
	v_cvt_pk_bf16_f32 v5, v38, v39
	v_cvt_pk_bf16_f32 v6, v68, v69
	v_cvt_pk_bf16_f32 v7, v70, v40
	v_accvgpr_read_b32 v20, a168
	v_exp_f32_e32 v97, v32
	v_cvt_pk_bf16_f32 v32, v87, v88
	v_cvt_pk_bf16_f32 v33, v89, v90
	v_cvt_pk_bf16_f32 v34, v91, v92
	v_cvt_pk_bf16_f32 v35, v93, v94
	v_exp_f32_e32 v95, v20
	ds_read_b128 v[20:23], v83 offset:36960
	v_mfma_f32_32x32x16_bf16 a[144:159], v[28:31], v[4:7], a[144:159]
	v_accvgpr_read_b32 v0, a187
	v_exp_f32_e32 v48, v0
	v_cvt_pk_bf16_f32 v0, v41, v42
	v_cvt_pk_bf16_f32 v1, v43, v44
	v_cvt_pk_bf16_f32 v2, v45, v46
	v_cvt_pk_bf16_f32 v3, v47, v48
	v_cvt_pk_bf16_f32 v130, v95, v96
	v_mfma_f32_32x32x16_bf16 a[128:143], v[28:31], v[32:35], a[128:143]
	v_accvgpr_read_b32 v28, a171
	v_exp_f32_e32 v98, v28
	v_accvgpr_read_b32 v28, a172
	v_exp_f32_e32 v99, v28
	v_accvgpr_read_b32 v28, a173
	v_exp_f32_e32 v100, v28
	v_accvgpr_read_b32 v28, a174
	v_exp_f32_e32 v101, v28
	v_accvgpr_read_b32 v28, a175
	v_exp_f32_e32 v102, v28
	v_cvt_pk_bf16_f32 v131, v97, v98
	v_cvt_pk_bf16_f32 v132, v99, v100
	s_waitcnt lgkmcnt(0)
	v_mfma_f32_32x32x16_bf16 a[144:159], v[20:23], v[0:3], a[144:159]
	v_cvt_pk_bf16_f32 v133, v101, v102
	s_nop 1
	v_mfma_f32_32x32x16_bf16 a[128:143], v[20:23], v[130:133], a[128:143]
	ds_read_b128 v[20:23], v83 offset:41472
	ds_read_b128 v[28:31], v83 offset:41504
	s_nop 5
	v_accvgpr_read_b32 v112, a144
	v_accvgpr_read_b32 v113, a145
	v_accvgpr_read_b32 v114, a146
	v_accvgpr_read_b32 v115, a147
	s_waitcnt lgkmcnt(1)
	v_mfma_f32_32x32x16_bf16 a[112:127], v[20:23], v[12:15], a[48:63]
	v_accvgpr_read_b32 v116, a148
	v_accvgpr_read_b32 v117, a149
	v_accvgpr_read_b32 v118, a150
	v_accvgpr_read_b32 v119, a151
	v_accvgpr_read_b32 v120, a152
	v_accvgpr_read_b32 v121, a153
	v_accvgpr_read_b32 v122, a154
	v_mfma_f32_32x32x16_bf16 a[48:63], v[20:23], v[24:27], a[64:79]
	v_accvgpr_read_b32 v123, a155
	v_accvgpr_read_b32 v124, a156
	v_accvgpr_read_b32 v125, a157
	v_accvgpr_read_b32 v126, a158
	v_accvgpr_read_b32 v127, a159
	s_waitcnt lgkmcnt(0)
	v_mfma_f32_32x32x16_bf16 a[112:127], v[28:31], v[8:11], a[112:127]
	v_mfma_f32_32x32x16_bf16 a[48:63], v[28:31], v[16:19], a[48:63]
	ds_read_b128 v[20:23], v83 offset:41536
	ds_read_b128 v[28:31], v83 offset:41568
	s_waitcnt lgkmcnt(1)
	v_mfma_f32_32x32x16_bf16 a[112:127], v[20:23], v[4:7], a[112:127]
	v_mfma_f32_32x32x16_bf16 a[48:63], v[20:23], v[32:35], a[48:63]
	s_waitcnt lgkmcnt(0)
	v_mfma_f32_32x32x16_bf16 a[112:127], v[28:31], v[0:3], a[112:127]
	v_mfma_f32_32x32x16_bf16 a[48:63], v[28:31], v[130:133], a[48:63]
	ds_read_b128 v[20:23], v83 offset:46080
	ds_read_b128 v[28:31], v83 offset:46112
	s_waitcnt lgkmcnt(1)
	v_mfma_f32_32x32x16_bf16 a[64:79], v[20:23], v[12:15], a[80:95]
	v_mfma_f32_32x32x16_bf16 a[80:95], v[20:23], v[24:27], a[96:111]
	ds_read_b128 v[20:23], v83 offset:46144
	s_waitcnt lgkmcnt(1)
	v_mfma_f32_32x32x16_bf16 a[64:79], v[28:31], v[8:11], a[64:79]
	v_mfma_f32_32x32x16_bf16 a[80:95], v[28:31], v[16:19], a[80:95]
	v_add_f32_e32 v28, 0, v52
	v_add_f32_e32 v28, v53, v28
	v_add_f32_e32 v28, v54, v28
	v_add_f32_e32 v28, v55, v28
	v_add_f32_e32 v52, v56, v28
	v_add_f32_e32 v52, v57, v52
	v_add_f32_e32 v52, v58, v52
	v_add_f32_e32 v52, v59, v52
	v_add_f32_e32 v52, v60, v52
	v_add_f32_e32 v52, v61, v52
	v_add_f32_e32 v52, v62, v52
	v_add_f32_e32 v52, v63, v52
	ds_read_b128 v[28:31], v83 offset:46176
	s_waitcnt lgkmcnt(1)
	v_mfma_f32_32x32x16_bf16 a[64:79], v[20:23], v[4:7], a[64:79]
	v_mfma_f32_32x32x16_bf16 a[80:95], v[20:23], v[32:35], a[80:95]
	v_add_f32_e32 v20, v64, v52
	v_add_f32_e32 v20, v65, v20
	v_add_f32_e32 v20, v66, v20
	v_add_f32_e32 v20, v67, v20
	v_add_f32_e32 v20, v36, v20
	v_add_f32_e32 v20, v37, v20
	v_add_f32_e32 v20, v38, v20
	v_add_f32_e32 v20, v39, v20
	v_add_f32_e32 v20, v68, v20
	v_add_f32_e32 v20, v69, v20
	v_add_f32_e32 v20, v70, v20
	v_add_f32_e32 v20, v40, v20
	v_add_f32_e32 v36, v41, v20
	ds_read_b128 v[20:23], v83 offset:50688
	s_waitcnt lgkmcnt(1)
	v_mfma_f32_32x32x16_bf16 a[64:79], v[28:31], v[0:3], a[64:79]
	v_mfma_f32_32x32x16_bf16 a[80:95], v[28:31], v[130:133], a[80:95]
	v_add_f32_e32 v28, v42, v36
	v_add_f32_e32 v28, v43, v28
	v_add_f32_e32 v28, v44, v28
	v_add_f32_e32 v28, v45, v28
	v_add_f32_e32 v28, v46, v28
	v_add_f32_e32 v36, v47, v28
	ds_read_b128 v[28:31], v83 offset:50720
	s_waitcnt lgkmcnt(1)
	v_mfma_f32_32x32x16_bf16 a[96:111], v[20:23], v[12:15], a[32:47]
	v_add_f32_e32 v12, v48, v36
	v_add_f32_e32 v136, v81, v12
	v_add_f32_e32 v12, 0, v49
	v_add_f32_e32 v12, v50, v12
	v_add_f32_e32 v12, v51, v12
	v_add_f32_e32 v12, v71, v12
	v_add_f32_e32 v12, v72, v12
	v_add_f32_e32 v12, v73, v12
	v_add_f32_e32 v12, v74, v12
	v_add_f32_e32 v12, v75, v12
	v_add_f32_e32 v12, v76, v12
	v_add_f32_e32 v12, v77, v12
	v_add_f32_e32 v12, v78, v12
	v_add_f32_e32 v12, v79, v12
	s_waitcnt lgkmcnt(0)
	v_mfma_f32_32x32x16_bf16 a[96:111], v[28:31], v[8:11], a[96:111]
	v_add_f32_e32 v8, v82, v12
	v_add_f32_e32 v8, v84, v8
	v_add_f32_e32 v8, v85, v8
	v_add_f32_e32 v8, v86, v8
	v_add_f32_e32 v8, v87, v8
	v_add_f32_e32 v12, v88, v8
	ds_read_b128 v[8:11], v83 offset:50752
	v_mfma_f32_32x32x16_bf16 a[32:47], v[20:23], v[24:27], a[16:31]
	v_add_f32_e32 v12, v89, v12
	v_add_f32_e32 v12, v90, v12
	v_add_f32_e32 v12, v91, v12
	v_add_f32_e32 v12, v92, v12
	v_add_f32_e32 v12, v93, v12
	v_accvgpr_read_b32 v48, a128
	v_accvgpr_read_b32 v49, a129
	v_mfma_f32_32x32x16_bf16 a[32:47], v[28:31], v[16:19], a[32:47]
	v_add_f32_e32 v16, v94, v12
	ds_read_b128 v[12:15], v83 offset:50784
	v_accvgpr_read_b32 v50, a130
	v_accvgpr_read_b32 v51, a131
	v_accvgpr_read_b32 v52, a132
	v_accvgpr_read_b32 v53, a133
	v_accvgpr_read_b32 v54, a134
	s_waitcnt lgkmcnt(1)
	v_mfma_f32_32x32x16_bf16 a[96:111], v[8:11], v[4:7], a[96:111]
	v_add_f32_e32 v4, v95, v16
	v_add_f32_e32 v4, v96, v4
	v_add_f32_e32 v4, v97, v4
	v_add_f32_e32 v4, v98, v4
	v_add_f32_e32 v4, v99, v4
	v_add_f32_e32 v4, v100, v4
	v_add_f32_e32 v4, v101, v4
	v_add_f32_e32 v4, v102, v4
	v_add_f32_e32 v137, v80, v4
	ds_bpermute_b32 v4, v159, v136
	v_mfma_f32_32x32x16_bf16 a[32:47], v[8:11], v[32:35], a[32:47]
	v_accvgpr_read_b32 v96, a112
	v_accvgpr_read_b32 v32, a48
	v_accvgpr_read_b32 v95, a79
	s_waitcnt lgkmcnt(0)
	v_add_f32_e32 v136, v136, v4
	v_div_scale_f32 v140, s[60:61], v136, v136, 1.0
	v_rcp_f32_e32 v141, v140
	v_mfma_f32_32x32x16_bf16 a[32:47], v[12:15], v[130:133], a[32:47]
	ds_bpermute_b32 v131, v159, v137
	v_accvgpr_read_b32 v16, a80
	v_fma_f32 v130, -v140, v141, 1.0
	v_fmac_f32_e32 v141, v130, v141
	v_div_scale_f32 v130, vcc, 1.0, v136, 1.0
	v_mul_f32_e32 v132, v130, v141
	v_fma_f32 v133, -v140, v132, v130
	s_waitcnt lgkmcnt(0)
	v_add_f32_e32 v131, v137, v131
	v_fmac_f32_e32 v132, v133, v141
	v_div_scale_f32 v133, s[60:61], v131, v131, 1.0
	v_rcp_f32_e32 v137, v133
	v_mfma_f32_32x32x16_bf16 a[96:111], v[12:15], v[0:3], a[96:111]
	v_fma_f32 v130, -v140, v132, v130
	v_div_fmas_f32 v130, v130, v141, v132
	v_div_fixup_f32 v222, v130, v136, 1.0
	v_fma_f32 v130, -v133, v137, 1.0
	v_fmac_f32_e32 v137, v130, v137
	v_div_scale_f32 v130, vcc, 1.0, v131, 1.0
	v_mul_f32_e32 v132, v130, v137
	v_fma_f32 v136, -v133, v132, v130
	v_fmac_f32_e32 v132, v136, v137
	v_fma_f32 v130, -v133, v132, v130
	v_accvgpr_read_b32 v0, a32
	s_nop 0
	v_accvgpr_read_b32 v64, a96
	v_div_fmas_f32 v130, v130, v137, v132
	v_accvgpr_read_b32 v55, a135
	v_accvgpr_read_b32 v56, a136
	v_accvgpr_read_b32 v57, a137
	v_accvgpr_read_b32 v58, a138
	v_accvgpr_read_b32 v59, a139
	v_accvgpr_read_b32 v60, a140
	v_accvgpr_read_b32 v61, a141
	v_accvgpr_read_b32 v62, a142
	v_accvgpr_read_b32 v63, a143
	v_accvgpr_read_b32 v97, a113
	v_accvgpr_read_b32 v98, a114
	v_accvgpr_read_b32 v99, a115
	v_accvgpr_read_b32 v100, a116
	v_accvgpr_read_b32 v101, a117
	v_accvgpr_read_b32 v102, a118
	v_accvgpr_read_b32 v103, a119
	v_accvgpr_read_b32 v104, a120
	v_accvgpr_read_b32 v105, a121
	v_accvgpr_read_b32 v106, a122
	v_accvgpr_read_b32 v107, a123
	v_accvgpr_read_b32 v108, a124
	v_accvgpr_read_b32 v109, a125
	v_accvgpr_read_b32 v110, a126
	v_accvgpr_read_b32 v111, a127
	v_accvgpr_read_b32 v33, a49
	v_accvgpr_read_b32 v34, a50
	v_accvgpr_read_b32 v35, a51
	v_accvgpr_read_b32 v36, a52
	v_accvgpr_read_b32 v37, a53
	v_accvgpr_read_b32 v38, a54
	v_accvgpr_read_b32 v39, a55
	v_accvgpr_read_b32 v40, a56
	v_accvgpr_read_b32 v41, a57
	v_accvgpr_read_b32 v42, a58
	v_accvgpr_read_b32 v43, a59
	v_accvgpr_read_b32 v44, a60
	v_accvgpr_read_b32 v45, a61
	v_accvgpr_read_b32 v46, a62
	v_accvgpr_read_b32 v47, a63
	v_accvgpr_read_b32 v94, a78
	v_accvgpr_read_b32 v93, a77
	v_accvgpr_read_b32 v92, a76
	v_accvgpr_read_b32 v91, a75
	v_accvgpr_read_b32 v90, a74
	v_accvgpr_read_b32 v89, a73
	v_accvgpr_read_b32 v88, a72
	v_accvgpr_read_b32 v87, a71
	v_accvgpr_read_b32 v86, a70
	v_accvgpr_read_b32 v85, a69
	v_accvgpr_read_b32 v84, a68
	v_accvgpr_read_b32 v83, a67
	v_accvgpr_read_b32 v82, a66
	v_accvgpr_read_b32 v81, a65
	v_accvgpr_read_b32 v80, a64
	v_accvgpr_read_b32 v17, a81
	v_accvgpr_read_b32 v18, a82
	v_accvgpr_read_b32 v19, a83
	v_accvgpr_read_b32 v20, a84
	v_accvgpr_read_b32 v21, a85
	v_accvgpr_read_b32 v22, a86
	v_accvgpr_read_b32 v23, a87
	v_accvgpr_read_b32 v24, a88
	v_accvgpr_read_b32 v25, a89
	v_accvgpr_read_b32 v26, a90
	v_accvgpr_read_b32 v27, a91
	v_accvgpr_read_b32 v28, a92
	v_accvgpr_read_b32 v29, a93
	v_accvgpr_read_b32 v30, a94
	v_accvgpr_read_b32 v31, a95
	v_accvgpr_read_b32 v65, a97
	v_accvgpr_read_b32 v66, a98
	v_accvgpr_read_b32 v67, a99
	v_accvgpr_read_b32 v68, a100
	v_accvgpr_read_b32 v69, a101
	v_accvgpr_read_b32 v70, a102
	v_accvgpr_read_b32 v71, a103
	v_accvgpr_read_b32 v72, a104
	v_accvgpr_read_b32 v73, a105
	v_accvgpr_read_b32 v74, a106
	v_accvgpr_read_b32 v75, a107
	v_accvgpr_read_b32 v76, a108
	v_accvgpr_read_b32 v77, a109
	v_accvgpr_read_b32 v78, a110
	v_accvgpr_read_b32 v79, a111
	v_accvgpr_read_b32 v1, a33
	v_accvgpr_read_b32 v2, a34
	v_accvgpr_read_b32 v3, a35
	v_accvgpr_read_b32 v4, a36
	v_accvgpr_read_b32 v5, a37
	v_accvgpr_read_b32 v6, a38
	v_accvgpr_read_b32 v7, a39
	v_accvgpr_read_b32 v8, a40
	v_accvgpr_read_b32 v9, a41
	v_accvgpr_read_b32 v10, a42
	v_accvgpr_read_b32 v11, a43
	v_accvgpr_read_b32 v12, a44
	v_accvgpr_read_b32 v13, a45
	v_accvgpr_read_b32 v14, a46
	v_accvgpr_read_b32 v15, a47
	v_div_fixup_f32 v168, v130, v131, 1.0
	s_barrier
	s_and_saveexec_b64 s[60:61], s[6:7]
	s_cbranch_execz .LBB0_2274
	v_accvgpr_read_b32 v133, a216
	v_mul_f32_e32 v130, v133, v222
	v_mul_f32_e32 v131, v112, v130
	v_mul_f32_e32 v132, v113, v130
	ds_write2st64_b32 v139, v131, v132 offset1:1
	v_mul_f32_e32 v131, v114, v130
	v_mul_f32_e32 v132, v115, v130
	ds_write2st64_b32 v139, v131, v132 offset0:2 offset1:3
	v_mul_f32_e32 v131, v116, v130
	v_mul_f32_e32 v132, v117, v130
	ds_write2st64_b32 v139, v131, v132 offset0:4 offset1:5
	v_mul_f32_e32 v131, v118, v130
	v_mul_f32_e32 v132, v119, v130
	ds_write2st64_b32 v139, v131, v132 offset0:6 offset1:7
	v_mul_f32_e32 v131, v120, v130
	v_mul_f32_e32 v132, v121, v130
	ds_write2st64_b32 v139, v131, v132 offset0:8 offset1:9
	v_mul_f32_e32 v131, v122, v130
	v_mul_f32_e32 v132, v123, v130
	ds_write2st64_b32 v139, v131, v132 offset0:10 offset1:11
	v_mul_f32_e32 v131, v124, v130
	v_mul_f32_e32 v132, v125, v130
	ds_write2st64_b32 v139, v131, v132 offset0:12 offset1:13
	v_mul_f32_e32 v131, v126, v130
	v_mul_f32_e32 v132, v127, v130
	ds_write2st64_b32 v139, v131, v132 offset0:14 offset1:15
	v_mul_f32_e32 v131, v96, v130
	v_mul_f32_e32 v132, v97, v130
	ds_write2st64_b32 v139, v131, v132 offset0:16 offset1:17
	v_mul_f32_e32 v131, v98, v130
	v_mul_f32_e32 v132, v99, v130
	ds_write2st64_b32 v139, v131, v132 offset0:18 offset1:19
	v_mul_f32_e32 v131, v100, v130
	v_mul_f32_e32 v132, v101, v130
	ds_write2st64_b32 v139, v131, v132 offset0:20 offset1:21
	v_mul_f32_e32 v131, v102, v130
	v_mul_f32_e32 v132, v103, v130
	ds_write2st64_b32 v139, v131, v132 offset0:22 offset1:23
	v_mul_f32_e32 v131, v104, v130
	v_mul_f32_e32 v132, v105, v130
	ds_write2st64_b32 v139, v131, v132 offset0:24 offset1:25
	v_mul_f32_e32 v131, v106, v130
	v_mul_f32_e32 v132, v107, v130
	ds_write2st64_b32 v139, v131, v132 offset0:26 offset1:27
	v_mul_f32_e32 v131, v108, v130
	v_mul_f32_e32 v132, v109, v130
	ds_write2st64_b32 v139, v131, v132 offset0:28 offset1:29
	v_mul_f32_e32 v131, v110, v130
	v_mul_f32_e32 v132, v111, v130
	ds_write2st64_b32 v139, v131, v132 offset0:30 offset1:31
	v_mul_f32_e32 v131, v80, v130
	v_mul_f32_e32 v132, v81, v130
	ds_write2st64_b32 v139, v131, v132 offset0:32 offset1:33
	v_mul_f32_e32 v131, v82, v130
	v_mul_f32_e32 v132, v83, v130
	ds_write2st64_b32 v139, v131, v132 offset0:34 offset1:35
	v_mul_f32_e32 v131, v84, v130
	v_mul_f32_e32 v132, v85, v130
	ds_write2st64_b32 v139, v131, v132 offset0:36 offset1:37
	v_mul_f32_e32 v131, v86, v130
	v_mul_f32_e32 v132, v87, v130
	ds_write2st64_b32 v139, v131, v132 offset0:38 offset1:39
	v_mul_f32_e32 v131, v88, v130
	v_mul_f32_e32 v132, v89, v130
	ds_write2st64_b32 v139, v131, v132 offset0:40 offset1:41
	v_mul_f32_e32 v131, v90, v130
	v_mul_f32_e32 v132, v91, v130
	ds_write2st64_b32 v139, v131, v132 offset0:42 offset1:43
	v_mul_f32_e32 v131, v92, v130
	v_mul_f32_e32 v132, v93, v130
	ds_write2st64_b32 v139, v131, v132 offset0:44 offset1:45
	v_mul_f32_e32 v131, v94, v130
	v_mul_f32_e32 v132, v95, v130
	ds_write2st64_b32 v139, v131, v132 offset0:46 offset1:47
	v_mul_f32_e32 v131, v64, v130
	v_mul_f32_e32 v132, v65, v130
	ds_write2st64_b32 v139, v131, v132 offset0:48 offset1:49
	v_mul_f32_e32 v131, v66, v130
	v_mul_f32_e32 v132, v67, v130
	ds_write2st64_b32 v139, v131, v132 offset0:50 offset1:51
	v_mul_f32_e32 v131, v68, v130
	v_mul_f32_e32 v132, v69, v130
	ds_write2st64_b32 v139, v131, v132 offset0:52 offset1:53
	v_mul_f32_e32 v131, v70, v130
	v_mul_f32_e32 v132, v71, v130
	ds_write2st64_b32 v139, v131, v132 offset0:54 offset1:55
	v_mul_f32_e32 v131, v72, v130
	v_mul_f32_e32 v132, v73, v130
	ds_write2st64_b32 v139, v131, v132 offset0:56 offset1:57
	v_mul_f32_e32 v131, v74, v130
	v_mul_f32_e32 v132, v75, v130
	ds_write2st64_b32 v139, v131, v132 offset0:58 offset1:59
	v_mul_f32_e32 v131, v76, v130
	v_mul_f32_e32 v132, v77, v130
	ds_write2st64_b32 v139, v131, v132 offset0:60 offset1:61
	v_mul_f32_e32 v131, v78, v130
	v_mul_f32_e32 v130, v79, v130
	ds_write2st64_b32 v139, v131, v130 offset0:62 offset1:63
	v_mul_f32_e32 v130, v133, v168
	v_mul_f32_e32 v131, v48, v130
	v_mul_f32_e32 v132, v49, v130
	ds_write2st64_b32 v254, v131, v132 offset1:1
	v_mul_f32_e32 v131, v50, v130
	v_mul_f32_e32 v132, v51, v130
	ds_write2st64_b32 v254, v131, v132 offset0:2 offset1:3
	v_mul_f32_e32 v131, v52, v130
	v_mul_f32_e32 v132, v53, v130
	ds_write2st64_b32 v254, v131, v132 offset0:4 offset1:5
	v_mul_f32_e32 v131, v54, v130
	v_mul_f32_e32 v132, v55, v130
	ds_write2st64_b32 v254, v131, v132 offset0:6 offset1:7
	v_mul_f32_e32 v131, v56, v130
	v_mul_f32_e32 v132, v57, v130
	ds_write2st64_b32 v254, v131, v132 offset0:8 offset1:9
	v_mul_f32_e32 v131, v58, v130
	v_mul_f32_e32 v132, v59, v130
	ds_write2st64_b32 v254, v131, v132 offset0:10 offset1:11
	v_mul_f32_e32 v131, v60, v130
	v_mul_f32_e32 v132, v61, v130
	ds_write2st64_b32 v254, v131, v132 offset0:12 offset1:13
	v_mul_f32_e32 v131, v62, v130
	v_mul_f32_e32 v132, v63, v130
	ds_write2st64_b32 v254, v131, v132 offset0:14 offset1:15
	v_mul_f32_e32 v131, v32, v130
	v_mul_f32_e32 v132, v33, v130
	ds_write2st64_b32 v254, v131, v132 offset0:16 offset1:17
	v_mul_f32_e32 v131, v34, v130
	v_mul_f32_e32 v132, v35, v130
	ds_write2st64_b32 v254, v131, v132 offset0:18 offset1:19
	v_mul_f32_e32 v131, v36, v130
	v_mul_f32_e32 v132, v37, v130
	ds_write2st64_b32 v254, v131, v132 offset0:20 offset1:21
	v_mul_f32_e32 v131, v38, v130
	v_mul_f32_e32 v132, v39, v130
	ds_write2st64_b32 v254, v131, v132 offset0:22 offset1:23
	v_mul_f32_e32 v131, v40, v130
	v_mul_f32_e32 v132, v41, v130
	ds_write2st64_b32 v254, v131, v132 offset0:24 offset1:25
	v_mul_f32_e32 v131, v42, v130
	v_mul_f32_e32 v132, v43, v130
	ds_write2st64_b32 v254, v131, v132 offset0:26 offset1:27
	v_mul_f32_e32 v131, v44, v130
	v_mul_f32_e32 v132, v45, v130
	ds_write2st64_b32 v254, v131, v132 offset0:28 offset1:29
	v_mul_f32_e32 v131, v46, v130
	v_mul_f32_e32 v132, v47, v130
	ds_write2st64_b32 v254, v131, v132 offset0:30 offset1:31
	v_mul_f32_e32 v131, v16, v130
	v_mul_f32_e32 v132, v17, v130
	ds_write2st64_b32 v254, v131, v132 offset0:32 offset1:33
	v_mul_f32_e32 v131, v18, v130
	v_mul_f32_e32 v132, v19, v130
	ds_write2st64_b32 v254, v131, v132 offset0:34 offset1:35
	v_mul_f32_e32 v131, v20, v130
	v_mul_f32_e32 v132, v21, v130
	ds_write2st64_b32 v254, v131, v132 offset0:36 offset1:37
	v_mul_f32_e32 v131, v22, v130
	v_mul_f32_e32 v132, v23, v130
	ds_write2st64_b32 v254, v131, v132 offset0:38 offset1:39
	v_mul_f32_e32 v131, v24, v130
	v_mul_f32_e32 v132, v25, v130
	ds_write2st64_b32 v254, v131, v132 offset0:40 offset1:41
	v_mul_f32_e32 v131, v26, v130
	v_mul_f32_e32 v132, v27, v130
	ds_write2st64_b32 v254, v131, v132 offset0:42 offset1:43
	v_mul_f32_e32 v131, v28, v130
	v_mul_f32_e32 v132, v29, v130
	ds_write2st64_b32 v254, v131, v132 offset0:44 offset1:45
	v_mul_f32_e32 v131, v30, v130
	v_mul_f32_e32 v132, v31, v130
	ds_write2st64_b32 v254, v131, v132 offset0:46 offset1:47
	v_mul_f32_e32 v131, v0, v130
	v_mul_f32_e32 v132, v1, v130
	ds_write2st64_b32 v254, v131, v132 offset0:48 offset1:49
	v_mul_f32_e32 v131, v2, v130
	v_mul_f32_e32 v132, v3, v130
	ds_write2st64_b32 v254, v131, v132 offset0:50 offset1:51
	v_mul_f32_e32 v131, v4, v130
	v_mul_f32_e32 v132, v5, v130
	ds_write2st64_b32 v254, v131, v132 offset0:52 offset1:53
	v_mul_f32_e32 v131, v6, v130
	v_mul_f32_e32 v132, v7, v130
	ds_write2st64_b32 v254, v131, v132 offset0:54 offset1:55
	v_mul_f32_e32 v131, v8, v130
	v_mul_f32_e32 v132, v9, v130
	ds_write2st64_b32 v254, v131, v132 offset0:56 offset1:57
	v_mul_f32_e32 v131, v10, v130
	v_mul_f32_e32 v132, v11, v130
	ds_write2st64_b32 v254, v131, v132 offset0:58 offset1:59
	v_mul_f32_e32 v131, v12, v130
	v_mul_f32_e32 v132, v13, v130
	ds_write2st64_b32 v254, v131, v132 offset0:60 offset1:61
	v_mul_f32_e32 v131, v14, v130
	v_mul_f32_e32 v130, v15, v130
	ds_write2st64_b32 v254, v131, v130 offset0:62 offset1:63
